# SwiGLU epilogues: all 16 v_mov+v_pk_mul swizzle sites per epilogue replaced by 2 v_mul (48 sites total)
# speedup vs baseline: 1.0019x; 1.0019x over previous
; #define PG8_STAGE(bufoff, gbase, voff) do { _Pragma("unroll") for (int _i = 0; _i < 2; ++_i) \
;         __builtin_amdgcn_global_load_lds((const unsigned*)((const char*)(gbase) + (voff)[_i]), (PG8_LAS unsigned*)(lds + (bufoff) + ldsw + _i * 8192), 16, 0, 0); } while (0)
; #define PG8_LDA(dst, b, h) do { _Pragma("unroll") for (int m = 0; m < 4; ++m) _Pragma("unroll") for (int k = 0; k < 2; ++k) dst[m][k] = *(const PG8_LAS bf16x8*)(lds + PG8_SA(b, h) + aoff + m * 2048 + k * 1024); } while (0)
; #define PG8_LDB(dst, b, h) do { _Pragma("unroll") for (int n = 0; n < 2; ++n) _Pragma("unroll") for (int k = 0; k < 2; ++k) dst[n][k] = *(const PG8_LAS bf16x8*)(lds + PG8_SB(b, h) + boff + n * 2048 + k * 1024); } while (0)
; #define PG8_MMA(ai, bj, At, Bt) do { __builtin_amdgcn_s_setprio(1); _Pragma("unroll") for (int m = 0; m < 4; ++m) _Pragma("unroll") for (int n = 0; n < 2; ++n) _Pragma("unroll") for (int k = 0; k < 2; ++k) \
;         acc[ai][bj][m][n] = __builtin_amdgcn_mfma_f32_16x16x32_bf16(Bt[n][k], At[m][k], acc[ai][bj][m][n], 0, 0, 0); __builtin_amdgcn_s_setprio(0); } while (0)
; #define PG8_WAIT_V(n) asm volatile("s_waitcnt vmcnt(" #n ")" ::: "memory")
; #define PG8_WAIT_L(n) asm volatile("s_waitcnt lgkmcnt(" #n ")" ::: "memory")
; template <class Epi, class Sched>
; __device__ __forceinline__ void gemm_phase(PG8_LAS unsigned char* lds, const Gemm g, const Sched& S, const Epi& E) {
;     ...
;             const bool last = (t == nt - 2);
;             const char* a1 = cA + (size_t)(t + 1) * kstep;
;             const char* a2 = last ? nA : cA + (size_t)(t + 2) * kstep; const char* b2 = last ? nB : cB + (size_t)(t + 2) * kstep;
;             const char* a3 = a2 + kstep; const char* b3 = b2 + kstep;
;             if (last && has_next) S.a_ready(nxt);
;             PG8_LDB(B0, 0, 0); PG8_SCHED; PG8_LDA(At, 0, 0); PG8_STAGE(PG8_SA(1, 1), a1 + hstep, voffA);
;             PG8_WAIT_L(8); PG8_BAR; PG8_WAIT_L(0); PG8_MMA(0, 0, At, B0); PG8_BAR; PG8_SCHED;
;             PG8_LDB(B1, 0, 1); PG8_STAGE(PG8_SB(0, 0), b2, voffB);
;             PG8_BAR; PG8_WAIT_L(0); PG8_MMA(0, 1, At, B1); PG8_BAR;
;             PG8_LDA(At, 0, 1); PG8_STAGE(PG8_SA(0, 0), a2, voffA);
;             PG8_BAR; PG8_WAIT_L(0); PG8_MMA(1, 0, At, B0); PG8_BAR; PG8_SCHED;
;             PG8_STAGE(PG8_SB(0, 1), b2 + hstep, voffB);
;             PG8_WAIT_V(6); PG8_BAR; PG8_MMA(1, 1, At, B1); PG8_BAR;
.LBB0_195:
	ds_read_b128 v[144:147], v151
	ds_read_b128 v[156:159], v151 offset:1024
	ds_read_b128 v[160:163], v151 offset:2048
	ds_read_b128 v[166:169], v151 offset:3072
	s_add_u32 s30, s28, 0xfffc0080
	s_addc_u32 s31, s29, -1
	s_cmp_eq_u32 s58, 12
	s_cselect_b32 s35, s17, s31
	s_cselect_b32 s34, s54, s30
	s_cselect_b32 s31, s15, s57
	s_cselect_b32 s30, s55, s56
	s_add_i32 m0, s27, 0xc000
	ds_read_b128 v[170:173], v153
	ds_read_b128 v[182:185], v153 offset:1024
	ds_read_b128 v[190:193], v153 offset:2048
	ds_read_b128 v[194:197], v153 offset:3072
	ds_read_b128 v[198:201], v153 offset:4096
	ds_read_b128 v[202:205], v153 offset:5120
	ds_read_b128 v[206:209], v153 offset:6144
	ds_read_b128 v[210:213], v153 offset:7168
	global_load_lds_dwordx4 v136, s[28:29]
	s_nop 1
	s_add_i32 m0, s27, 0xe000
	s_nop 0
	global_load_lds_dwordx4 v138, s[28:29]
	s_waitcnt lgkmcnt(8)
	ds_read_b128 v[214:217], v154
	ds_read_b128 v[218:221], v154 offset:1024
	ds_read_b128 v[222:225], v154 offset:2048
	ds_read_b128 v[226:229], v154 offset:3072
	s_waitcnt vmcnt(8) lgkmcnt(0)
	s_barrier
	v_mfma_f32_16x16x32_bf16 v[124:127], v[144:147], v[170:173], v[124:127]
	v_mfma_f32_16x16x32_bf16 v[120:123], v[160:163], v[170:173], v[120:123]
	v_mfma_f32_16x16x32_bf16 v[108:111], v[144:147], v[190:193], v[108:111]
	v_mfma_f32_16x16x32_bf16 v[104:107], v[160:163], v[190:193], v[104:107]
	v_mfma_f32_16x16x32_bf16 v[92:95], v[144:147], v[198:201], v[92:95]
	v_mfma_f32_16x16x32_bf16 v[88:91], v[160:163], v[198:201], v[88:91]
	v_mfma_f32_16x16x32_bf16 v[76:79], v[144:147], v[206:209], v[76:79]
	v_mfma_f32_16x16x32_bf16 v[72:75], v[160:163], v[206:209], v[72:75]
	v_mfma_f32_16x16x32_bf16 v[124:127], v[156:159], v[182:185], v[124:127]
	v_mfma_f32_16x16x32_bf16 v[120:123], v[166:169], v[182:185], v[120:123]
	v_mfma_f32_16x16x32_bf16 v[108:111], v[156:159], v[194:197], v[108:111]
	v_mfma_f32_16x16x32_bf16 v[104:107], v[166:169], v[194:197], v[104:107]
	v_mfma_f32_16x16x32_bf16 v[92:95], v[156:159], v[202:205], v[92:95]
	v_mfma_f32_16x16x32_bf16 v[88:91], v[166:169], v[202:205], v[88:91]
	v_mfma_f32_16x16x32_bf16 v[76:79], v[156:159], v[210:213], v[76:79]
	v_mfma_f32_16x16x32_bf16 v[72:75], v[166:169], v[210:213], v[72:75]
	v_mfma_f32_16x16x32_bf16 v[116:119], v[214:217], v[170:173], v[116:119]
	v_mfma_f32_16x16x32_bf16 v[112:115], v[222:225], v[170:173], v[112:115]
	v_mfma_f32_16x16x32_bf16 v[100:103], v[214:217], v[190:193], v[100:103]
	v_mfma_f32_16x16x32_bf16 v[96:99], v[222:225], v[190:193], v[96:99]
	v_mfma_f32_16x16x32_bf16 v[84:87], v[214:217], v[198:201], v[84:87]
	v_mfma_f32_16x16x32_bf16 v[80:83], v[222:225], v[198:201], v[80:83]
	v_mfma_f32_16x16x32_bf16 v[68:71], v[214:217], v[206:209], v[68:71]
	v_mfma_f32_16x16x32_bf16 v[64:67], v[222:225], v[206:209], v[64:67]
	v_mfma_f32_16x16x32_bf16 v[116:119], v[218:221], v[182:185], v[116:119]
	v_mfma_f32_16x16x32_bf16 v[112:115], v[226:229], v[182:185], v[112:115]
	v_mfma_f32_16x16x32_bf16 v[100:103], v[218:221], v[194:197], v[100:103]
	v_mfma_f32_16x16x32_bf16 v[96:99], v[226:229], v[194:197], v[96:99]
	v_mfma_f32_16x16x32_bf16 v[84:87], v[218:221], v[202:205], v[84:87]
	v_mfma_f32_16x16x32_bf16 v[80:83], v[226:229], v[202:205], v[80:83]
	v_mfma_f32_16x16x32_bf16 v[68:71], v[218:221], v[210:213], v[68:71]
	v_mfma_f32_16x16x32_bf16 v[64:67], v[226:229], v[210:213], v[64:67]
	s_barrier
	ds_read_b128 v[170:173], v153 offset:16384
	ds_read_b128 v[182:185], v153 offset:17408
	ds_read_b128 v[190:193], v153 offset:18432
	ds_read_b128 v[194:197], v153 offset:19456
	ds_read_b128 v[198:201], v153 offset:20480
	ds_read_b128 v[202:205], v153 offset:21504
	ds_read_b128 v[206:209], v153 offset:22528
	ds_read_b128 v[210:213], v153 offset:23552
	s_add_i32 s59, s50, s40
	s_add_u32 s98, s30, s10
	s_addc_u32 s99, s31, s11
	s_mov_b32 m0, s59
	s_nop 0
	global_load_lds_dwordx4 v132, s[30:31]
	s_nop 1
	s_add_i32 m0, s59, 0x2000
	s_nop 0
	global_load_lds_dwordx4 v128, s[30:31]
	s_nop 1
	s_mov_b32 m0, s27
	s_add_u32 s100, s34, s10
	s_addc_u32 s101, s35, s11
	global_load_lds_dwordx4 v134, s[34:35]
	s_nop 1
	s_mov_b32 m0, s43
	s_nop 0
	global_load_lds_dwordx4 v130, s[34:35]
	s_add_u32 s60, s30, 0x40000
	s_addc_u32 s61, s31, 0
	s_add_i32 s59, s51, s40
	s_mov_b32 m0, s59
	s_nop 0
	global_load_lds_dwordx4 v132, s[60:61]
	s_nop 1
	s_add_i32 m0, s59, 0x2000
	s_nop 0
	global_load_lds_dwordx4 v128, s[60:61]
	s_waitcnt vmcnt(8) lgkmcnt(0)
	s_barrier
	v_mfma_f32_16x16x32_bf16 v[60:63], v[144:147], v[170:173], v[60:63]
	v_mfma_f32_16x16x32_bf16 v[56:59], v[160:163], v[170:173], v[56:59]
	v_mfma_f32_16x16x32_bf16 v[44:47], v[144:147], v[190:193], v[44:47]
	v_mfma_f32_16x16x32_bf16 v[40:43], v[160:163], v[190:193], v[40:43]
	v_mfma_f32_16x16x32_bf16 v[28:31], v[144:147], v[198:201], v[28:31]
	v_mfma_f32_16x16x32_bf16 v[24:27], v[160:163], v[198:201], v[24:27]
	v_mfma_f32_16x16x32_bf16 v[12:15], v[144:147], v[206:209], v[12:15]
	v_mfma_f32_16x16x32_bf16 v[8:11], v[160:163], v[206:209], v[8:11]
	v_mfma_f32_16x16x32_bf16 v[60:63], v[156:159], v[182:185], v[60:63]
	v_mfma_f32_16x16x32_bf16 v[56:59], v[166:169], v[182:185], v[56:59]
	v_mfma_f32_16x16x32_bf16 v[44:47], v[156:159], v[194:197], v[44:47]
	v_mfma_f32_16x16x32_bf16 v[40:43], v[166:169], v[194:197], v[40:43]
	v_mfma_f32_16x16x32_bf16 v[28:31], v[156:159], v[202:205], v[28:31]
	v_mfma_f32_16x16x32_bf16 v[24:27], v[166:169], v[202:205], v[24:27]
	v_mfma_f32_16x16x32_bf16 v[12:15], v[156:159], v[210:213], v[12:15]
	v_mfma_f32_16x16x32_bf16 v[8:11], v[166:169], v[210:213], v[8:11]
	v_mfma_f32_16x16x32_bf16 v[52:55], v[214:217], v[170:173], v[52:55]
	v_mfma_f32_16x16x32_bf16 v[48:51], v[222:225], v[170:173], v[48:51]
	v_mfma_f32_16x16x32_bf16 v[36:39], v[214:217], v[190:193], v[36:39]
	v_mfma_f32_16x16x32_bf16 v[32:35], v[222:225], v[190:193], v[32:35]
	v_mfma_f32_16x16x32_bf16 v[20:23], v[214:217], v[198:201], v[20:23]
	v_mfma_f32_16x16x32_bf16 v[16:19], v[222:225], v[198:201], v[16:19]
	v_mfma_f32_16x16x32_bf16 v[4:7], v[214:217], v[206:209], v[4:7]
	v_mfma_f32_16x16x32_bf16 v[0:3], v[222:225], v[206:209], v[0:3]
	v_mfma_f32_16x16x32_bf16 v[52:55], v[218:221], v[182:185], v[52:55]
	v_mfma_f32_16x16x32_bf16 v[48:51], v[226:229], v[182:185], v[48:51]
	v_mfma_f32_16x16x32_bf16 v[36:39], v[218:221], v[194:197], v[36:39]
	v_mfma_f32_16x16x32_bf16 v[32:35], v[226:229], v[194:197], v[32:35]
	v_mfma_f32_16x16x32_bf16 v[20:23], v[218:221], v[202:205], v[20:23]
	v_mfma_f32_16x16x32_bf16 v[16:19], v[226:229], v[202:205], v[16:19]
	v_mfma_f32_16x16x32_bf16 v[4:7], v[218:221], v[210:213], v[4:7]
	v_mfma_f32_16x16x32_bf16 v[0:3], v[226:229], v[210:213], v[0:3]
	s_barrier
; #define PG8_STAGE(bufoff, gbase, voff) do { _Pragma("unroll") for (int _i = 0; _i < 2; ++_i) \
;         __builtin_amdgcn_global_load_lds((const unsigned*)((const char*)(gbase) + (voff)[_i]), (PG8_LAS unsigned*)(lds + (bufoff) + ldsw + _i * 8192), 16, 0, 0); } while (0)
; #define PG8_LDA(dst, b, h) do { _Pragma("unroll") for (int m = 0; m < 4; ++m) _Pragma("unroll") for (int k = 0; k < 2; ++k) dst[m][k] = *(const PG8_LAS bf16x8*)(lds + PG8_SA(b, h) + aoff + m * 2048 + k * 1024); } while (0)
; #define PG8_LDB(dst, b, h) do { _Pragma("unroll") for (int n = 0; n < 2; ++n) _Pragma("unroll") for (int k = 0; k < 2; ++k) dst[n][k] = *(const PG8_LAS bf16x8*)(lds + PG8_SB(b, h) + boff + n * 2048 + k * 1024); } while (0)
; #define PG8_MMA(ai, bj, At, Bt) do { __builtin_amdgcn_s_setprio(1); _Pragma("unroll") for (int m = 0; m < 4; ++m) _Pragma("unroll") for (int n = 0; n < 2; ++n) _Pragma("unroll") for (int k = 0; k < 2; ++k) \
;         acc[ai][bj][m][n] = __builtin_amdgcn_mfma_f32_16x16x32_bf16(Bt[n][k], At[m][k], acc[ai][bj][m][n], 0, 0, 0); __builtin_amdgcn_s_setprio(0); } while (0)
; #define PG8_WAIT_V(n) asm volatile("s_waitcnt vmcnt(" #n ")" ::: "memory")
; #define PG8_WAIT_L(n) asm volatile("s_waitcnt lgkmcnt(" #n ")" ::: "memory")
; #define PG8_BAR __builtin_amdgcn_s_barrier()
; #define PG8_SCHED __builtin_amdgcn_sched_barrier(0)
; template <class Epi, class Sched>
; __device__ __forceinline__ void gemm_phase(PG8_LAS unsigned char* lds, const Gemm g, const Sched& S, const Epi& E) {
;     ...
;             PG8_LDB(B0, 1, 0); PG8_SCHED; PG8_LDA(At, 1, 0); PG8_STAGE(PG8_SA(0, 1), a2 + hstep, voffA);
;             PG8_WAIT_L(8); PG8_BAR; PG8_WAIT_L(0); PG8_MMA(0, 0, At, B0); PG8_BAR; PG8_SCHED;
;             PG8_LDB(B1, 1, 1); PG8_STAGE(PG8_SB(1, 0), b3, voffB);
;             PG8_BAR; PG8_WAIT_L(0); PG8_MMA(0, 1, At, B1); PG8_BAR;
;             PG8_LDA(At, 1, 1); PG8_STAGE(PG8_SA(1, 0), a3, voffA);
;             PG8_BAR; PG8_WAIT_L(0); PG8_MMA(1, 0, At, B0); PG8_BAR; PG8_SCHED;
;             PG8_STAGE(PG8_SB(1, 1), b3 + hstep, voffB);
;             PG8_WAIT_V(6); PG8_BAR; PG8_MMA(1, 1, At, B1); PG8_BAR;
	s_add_i32 s59, 0, 0x18000
	v_add_u32_e32 v155, s59, v149
	ds_read_b128 v[144:147], v155
	ds_read_b128 v[156:159], v155 offset:1024
	ds_read_b128 v[160:163], v155 offset:2048
	ds_read_b128 v[166:169], v155 offset:3072
	s_add_u32 s34, s34, 0x40000
	s_addc_u32 s35, s35, 0
	s_mov_b32 m0, s44
	ds_read_b128 v[170:173], v153 offset:32768
	ds_read_b128 v[182:185], v153 offset:33792
	ds_read_b128 v[190:193], v153 offset:34816
	ds_read_b128 v[194:197], v153 offset:35840
	ds_read_b128 v[198:201], v153 offset:36864
	ds_read_b128 v[202:205], v153 offset:37888
	ds_read_b128 v[206:209], v153 offset:38912
	ds_read_b128 v[210:213], v153 offset:39936
	global_load_lds_dwordx4 v134, s[34:35]
	s_nop 1
	s_mov_b32 m0, s45
	s_nop 0
	global_load_lds_dwordx4 v130, s[34:35]
	s_add_i32 s34, 0, 0x1c000
	v_add_u32_e32 v155, s34, v149
	s_waitcnt lgkmcnt(8)
	ds_read_b128 v[214:217], v155
	ds_read_b128 v[218:221], v155 offset:1024
	ds_read_b128 v[222:225], v155 offset:2048
	ds_read_b128 v[226:229], v155 offset:3072
	s_waitcnt vmcnt(8) lgkmcnt(0)
	s_barrier
	v_mfma_f32_16x16x32_bf16 v[124:127], v[144:147], v[170:173], v[124:127]
	v_mfma_f32_16x16x32_bf16 v[120:123], v[160:163], v[170:173], v[120:123]
	v_mfma_f32_16x16x32_bf16 v[108:111], v[144:147], v[190:193], v[108:111]
	v_mfma_f32_16x16x32_bf16 v[104:107], v[160:163], v[190:193], v[104:107]
	v_mfma_f32_16x16x32_bf16 v[92:95], v[144:147], v[198:201], v[92:95]
	v_mfma_f32_16x16x32_bf16 v[88:91], v[160:163], v[198:201], v[88:91]
	v_mfma_f32_16x16x32_bf16 v[76:79], v[144:147], v[206:209], v[76:79]
	v_mfma_f32_16x16x32_bf16 v[72:75], v[160:163], v[206:209], v[72:75]
	v_mfma_f32_16x16x32_bf16 v[124:127], v[156:159], v[182:185], v[124:127]
	v_mfma_f32_16x16x32_bf16 v[120:123], v[166:169], v[182:185], v[120:123]
	v_mfma_f32_16x16x32_bf16 v[108:111], v[156:159], v[194:197], v[108:111]
	v_mfma_f32_16x16x32_bf16 v[104:107], v[166:169], v[194:197], v[104:107]
	v_mfma_f32_16x16x32_bf16 v[92:95], v[156:159], v[202:205], v[92:95]
	v_mfma_f32_16x16x32_bf16 v[88:91], v[166:169], v[202:205], v[88:91]
	v_mfma_f32_16x16x32_bf16 v[76:79], v[156:159], v[210:213], v[76:79]
	v_mfma_f32_16x16x32_bf16 v[72:75], v[166:169], v[210:213], v[72:75]
	v_mfma_f32_16x16x32_bf16 v[116:119], v[214:217], v[170:173], v[116:119]
	v_mfma_f32_16x16x32_bf16 v[112:115], v[222:225], v[170:173], v[112:115]
	v_mfma_f32_16x16x32_bf16 v[100:103], v[214:217], v[190:193], v[100:103]
	v_mfma_f32_16x16x32_bf16 v[96:99], v[222:225], v[190:193], v[96:99]
	v_mfma_f32_16x16x32_bf16 v[84:87], v[214:217], v[198:201], v[84:87]
	v_mfma_f32_16x16x32_bf16 v[80:83], v[222:225], v[198:201], v[80:83]
	v_mfma_f32_16x16x32_bf16 v[68:71], v[214:217], v[206:209], v[68:71]
	v_mfma_f32_16x16x32_bf16 v[64:67], v[222:225], v[206:209], v[64:67]
	v_mfma_f32_16x16x32_bf16 v[116:119], v[218:221], v[182:185], v[116:119]
	v_mfma_f32_16x16x32_bf16 v[112:115], v[226:229], v[182:185], v[112:115]
	v_mfma_f32_16x16x32_bf16 v[100:103], v[218:221], v[194:197], v[100:103]
	v_mfma_f32_16x16x32_bf16 v[96:99], v[226:229], v[194:197], v[96:99]
	v_mfma_f32_16x16x32_bf16 v[84:87], v[218:221], v[202:205], v[84:87]
	v_mfma_f32_16x16x32_bf16 v[80:83], v[226:229], v[202:205], v[80:83]
	v_mfma_f32_16x16x32_bf16 v[68:71], v[218:221], v[210:213], v[68:71]
	v_mfma_f32_16x16x32_bf16 v[64:67], v[226:229], v[210:213], v[64:67]
	s_barrier
	ds_read_b128 v[170:173], v153 offset:49152
	ds_read_b128 v[182:185], v153 offset:50176
	ds_read_b128 v[190:193], v153 offset:51200
	ds_read_b128 v[194:197], v153 offset:52224
	ds_read_b128 v[198:201], v153 offset:53248
	ds_read_b128 v[202:205], v153 offset:54272
	ds_read_b128 v[206:209], v153 offset:55296
	ds_read_b128 v[210:213], v153 offset:56320
	s_add_i32 s35, s59, s40
	s_mov_b32 m0, s35
	s_nop 0
	global_load_lds_dwordx4 v132, s[98:99]
	s_nop 1
	s_add_i32 m0, s35, 0x2000
	s_nop 0
	global_load_lds_dwordx4 v128, s[98:99]
	s_nop 1
	s_mov_b32 m0, s47
	s_nop 0
	global_load_lds_dwordx4 v134, s[100:101]
	s_nop 1
	s_mov_b32 m0, s48
	s_nop 0
	global_load_lds_dwordx4 v130, s[100:101]
	s_add_u32 s30, s30, 0x40080
	s_addc_u32 s31, s31, 0
	s_add_i32 s34, s34, s40
	s_mov_b32 m0, s34
	s_nop 0
	global_load_lds_dwordx4 v132, s[30:31]
	s_nop 1
	s_add_i32 m0, s34, 0x2000
	s_nop 0
	global_load_lds_dwordx4 v128, s[30:31]
	s_waitcnt vmcnt(8) lgkmcnt(0)
	s_barrier
	v_mfma_f32_16x16x32_bf16 v[60:63], v[144:147], v[170:173], v[60:63]
	v_mfma_f32_16x16x32_bf16 v[56:59], v[160:163], v[170:173], v[56:59]
	v_mfma_f32_16x16x32_bf16 v[44:47], v[144:147], v[190:193], v[44:47]
	v_mfma_f32_16x16x32_bf16 v[40:43], v[160:163], v[190:193], v[40:43]
	v_mfma_f32_16x16x32_bf16 v[28:31], v[144:147], v[198:201], v[28:31]
	v_mfma_f32_16x16x32_bf16 v[24:27], v[160:163], v[198:201], v[24:27]
	v_mfma_f32_16x16x32_bf16 v[12:15], v[144:147], v[206:209], v[12:15]
	v_mfma_f32_16x16x32_bf16 v[8:11], v[160:163], v[206:209], v[8:11]
	v_mfma_f32_16x16x32_bf16 v[60:63], v[156:159], v[182:185], v[60:63]
	v_mfma_f32_16x16x32_bf16 v[56:59], v[166:169], v[182:185], v[56:59]
	v_mfma_f32_16x16x32_bf16 v[44:47], v[156:159], v[194:197], v[44:47]
	v_mfma_f32_16x16x32_bf16 v[40:43], v[166:169], v[194:197], v[40:43]
	v_mfma_f32_16x16x32_bf16 v[28:31], v[156:159], v[202:205], v[28:31]
	v_mfma_f32_16x16x32_bf16 v[24:27], v[166:169], v[202:205], v[24:27]
	v_mfma_f32_16x16x32_bf16 v[12:15], v[156:159], v[210:213], v[12:15]
	v_mfma_f32_16x16x32_bf16 v[8:11], v[166:169], v[210:213], v[8:11]
	v_mfma_f32_16x16x32_bf16 v[52:55], v[214:217], v[170:173], v[52:55]
	v_mfma_f32_16x16x32_bf16 v[48:51], v[222:225], v[170:173], v[48:51]
	v_mfma_f32_16x16x32_bf16 v[36:39], v[214:217], v[190:193], v[36:39]
	v_mfma_f32_16x16x32_bf16 v[32:35], v[222:225], v[190:193], v[32:35]
	v_mfma_f32_16x16x32_bf16 v[20:23], v[214:217], v[198:201], v[20:23]
	v_mfma_f32_16x16x32_bf16 v[16:19], v[222:225], v[198:201], v[16:19]
	v_mfma_f32_16x16x32_bf16 v[4:7], v[214:217], v[206:209], v[4:7]
	v_mfma_f32_16x16x32_bf16 v[0:3], v[222:225], v[206:209], v[0:3]
	v_mfma_f32_16x16x32_bf16 v[52:55], v[218:221], v[182:185], v[52:55]
	v_mfma_f32_16x16x32_bf16 v[48:51], v[226:229], v[182:185], v[48:51]
	v_mfma_f32_16x16x32_bf16 v[36:39], v[218:221], v[194:197], v[36:39]
	v_mfma_f32_16x16x32_bf16 v[32:35], v[226:229], v[194:197], v[32:35]
	v_mfma_f32_16x16x32_bf16 v[20:23], v[218:221], v[202:205], v[20:23]
	v_mfma_f32_16x16x32_bf16 v[16:19], v[226:229], v[202:205], v[16:19]
	v_mfma_f32_16x16x32_bf16 v[4:7], v[218:221], v[210:213], v[4:7]
	v_mfma_f32_16x16x32_bf16 v[0:3], v[226:229], v[210:213], v[0:3]
	s_barrier
; __device__ __forceinline__ unsigned cvt_pk_bf16(float lo, float hi) { unsigned r; asm volatile("v_cvt_pk_bf16_f32 %0, %1, %2" : "=v"(r) : "v"(lo), "v"(hi)); return r; }
; __device__ __forceinline__ f32x4 sigmoid4(f32x4 x) {
;     f32x4 d;
; #pragma unroll
;     for (int j = 0; j < 4; ++j) d[j] = 1.0f + __expf(-fmaxf(x[j], -20.0f));
;     const float p01 = d[0] * d[1], p23 = d[2] * d[3], r = __builtin_amdgcn_rcpf(p01 * p23), r01 = r * p23, r23 = r * p01;
;     return (f32x4){r01 * d[1], r01 * d[0], r23 * d[3], r23 * d[2]};
; }
;     __device__ __forceinline__ void operator()(const f32x4 (&acc)[2][2][4][2], const Unit& u, int wr, int wc, int fr, int fq) const {
;         const int row0 = u.pm * BM + wr * 64 + fr, col0 = u.pn * HALF + wc * 32 + 8 * fq;
; #pragma unroll
;         for (int ai = 0; ai < 2; ++ai)
; #pragma unroll
;             for (int m = 0; m < 4; ++m) { bf16_t* rowp = O + (size_t)(row0 + ai * HALF + m * 16) * ldc + col0;
;                 f32x4 v0, v1;
; #pragma unroll
;                 for (int j = 0; j < 1; ++j) { v0 = acc[ai][0][m][0] * sigmoid4(acc[ai][0][m][0]) * acc[ai][1][m][0]; v1 = acc[ai][0][m][1] * sigmoid4(acc[ai][0][m][1]) * acc[ai][1][m][1]; }
;                 u32x4 w; w.x = cvt_pk_bf16(v0[0], v0[1]); w.y = cvt_pk_bf16(v0[2], v0[3]); w.z = cvt_pk_bf16(v1[0], v1[1]); w.w = cvt_pk_bf16(v1[2], v1[3]);
;                 *(u32x4*)rowp = w; }
	s_add_i32 s58, s58, 2
	s_add_u32 s28, s28, 0x100
	s_addc_u32 s29, s29, 0
	s_add_u32 s56, s56, 0x100
	s_addc_u32 s57, s57, 0
	s_cmp_gt_u32 s58, 13
	s_cbranch_scc0 .LBB0_195
	v_max_f32_e32 v144, 0xc1a00000, v124
	v_mul_f32_e32 v144, 0xbfb8aa3b, v144
	v_exp_f32_e32 v157, v144
	v_max_f32_e32 v144, 0xc1a00000, v125
	v_mul_f32_e32 v144, 0xbfb8aa3b, v144
	v_exp_f32_e32 v156, v144
	v_max_f32_e32 v144, 0xc1a00000, v126
	v_mul_f32_e32 v144, 0xbfb8aa3b, v144
	v_exp_f32_e32 v159, v144
	v_max_f32_e32 v144, 0xc1a00000, v127
	v_mul_f32_e32 v144, 0xbfb8aa3b, v144
	v_exp_f32_e32 v158, v144
	v_pk_add_f32 v[156:157], v[156:157], 1.0 op_sel_hi:[1,0]
	v_lshl_or_b32 v146, s53, 7, v150
	v_pk_add_f32 v[158:159], v[158:159], 1.0 op_sel_hi:[1,0]
	v_mul_f32_e32 v160, v157, v156
	v_mul_f32_e32 v161, v159, v158
	v_lshl_add_u32 v155, s26, 8, v148
	v_mul_f32_e32 v162, v160, v161
	v_rcp_f32_e32 v166, v162
	v_ashrrev_i32_e32 v147, 31, v146
	v_mov_b64_e32 v[144:145], s[4:5]
	v_mad_i64_i32 v[162:163], s[28:29], v155, s52, v[144:145]
	v_mul_f32_e32 v160, v160, v166
	v_mul_f32_e32 v164, v161, v166
	v_pk_mul_f32 v[158:159], v[158:159], v[160:161] op_sel_hi:[1,0]
	v_max_f32_e32 v160, 0xc1a00000, v120
	v_max_f32_e32 v166, 0xc1a00000, v122
	v_mul_f32_e32 v160, 0xbfb8aa3b, v160
	v_mul_f32_e32 v166, 0xbfb8aa3b, v166
	v_exp_f32_e32 v161, v160
	v_exp_f32_e32 v167, v166
	v_max_f32_e32 v160, 0xc1a00000, v121
	v_max_f32_e32 v166, 0xc1a00000, v123
	v_mul_f32_e32 v160, 0xbfb8aa3b, v160
	v_mul_f32_e32 v166, 0xbfb8aa3b, v166
	v_exp_f32_e32 v160, v160
	v_exp_f32_e32 v166, v166
	v_pk_mul_f32 v[156:157], v[156:157], v[164:165] op_sel_hi:[1,0]
	v_pk_mul_f32 v[126:127], v[126:127], v[158:159]
	v_pk_mul_f32 v[124:125], v[124:125], v[156:157]
	v_pk_add_f32 v[156:157], v[160:161], 1.0 op_sel_hi:[1,0]
	v_pk_add_f32 v[160:161], v[166:167], 1.0 op_sel_hi:[1,0]
	v_mul_f32_e32 v166, v157, v156
	v_mul_f32_e32 v167, v161, v160
	v_pk_mul_f32 v[118:119], v[126:127], v[118:119]
	v_mul_f32_e32 v164, v166, v167
	v_rcp_f32_e32 v164, v164
	v_pk_mul_f32 v[116:117], v[124:125], v[116:117]
	v_lshlrev_b64 v[146:147], 1, v[146:147]
	v_lshl_add_u64 v[162:163], v[162:163], 0, v[146:147]
	v_mul_f32_e32 v124, v167, v164
	v_mul_f32_e32 v126, v166, v164
	v_pk_mul_f32 v[126:127], v[160:161], v[126:127] op_sel_hi:[1,0]
	v_pk_mul_f32 v[124:125], v[156:157], v[124:125] op_sel_hi:[1,0]
	v_pk_mul_f32 v[122:123], v[122:123], v[126:127]
	v_pk_mul_f32 v[120:121], v[120:121], v[124:125]
	v_pk_mul_f32 v[122:123], v[122:123], v[114:115]
	v_pk_mul_f32 v[114:115], v[120:121], v[112:113]
	v_cvt_pk_bf16_f32 v112, v116, v117
	v_cvt_pk_bf16_f32 v113, v118, v119
	v_max_f32_e32 v116, 0xc1a00000, v108
	v_max_f32_e32 v118, 0xc1a00000, v110
	v_mul_f32_e32 v116, 0xbfb8aa3b, v116
	v_mul_f32_e32 v118, 0xbfb8aa3b, v118
	v_exp_f32_e32 v117, v116
	v_exp_f32_e32 v119, v118
	v_max_f32_e32 v116, 0xc1a00000, v109
	v_max_f32_e32 v118, 0xc1a00000, v111
	v_mul_f32_e32 v116, 0xbfb8aa3b, v116
	v_mul_f32_e32 v118, 0xbfb8aa3b, v118
	v_exp_f32_e32 v116, v116
	v_exp_f32_e32 v118, v118
	v_cvt_pk_bf16_f32 v114, v114, v115
	v_cvt_pk_bf16_f32 v115, v122, v123
	global_store_dwordx4 v[162:163], v[112:115], off
	v_or_b32_e32 v120, 16, v155
	s_and_b64 vcc, exec, s[2:3]
	v_pk_add_f32 v[112:113], v[116:117], 1.0 op_sel_hi:[1,0]
	v_pk_add_f32 v[114:115], v[118:119], 1.0 op_sel_hi:[1,0]
	v_mul_f32_e32 v116, v113, v112
	v_mul_f32_e32 v117, v115, v114
	s_mov_b32 s53, s14
	v_mul_f32_e32 v118, v116, v117
	v_rcp_f32_e32 v121, v118
	v_mad_i64_i32 v[118:119], s[28:29], v120, s52, v[144:145]
	v_lshl_add_u64 v[118:119], v[118:119], 0, v[146:147]
	v_mul_f32_e32 v116, v116, v121
	v_mul_f32_e32 v120, v117, v121
	v_pk_mul_f32 v[114:115], v[114:115], v[116:117] op_sel_hi:[1,0]
	v_max_f32_e32 v116, 0xc1a00000, v104
	v_max_f32_e32 v121, 0xc1a00000, v106
	v_mul_f32_e32 v116, 0xbfb8aa3b, v116
	v_mul_f32_e32 v121, 0xbfb8aa3b, v121
	v_exp_f32_e32 v117, v116
	v_exp_f32_e32 v123, v121
	v_max_f32_e32 v116, 0xc1a00000, v105
	v_max_f32_e32 v121, 0xc1a00000, v107
	v_mul_f32_e32 v116, 0xbfb8aa3b, v116
	v_mul_f32_e32 v121, 0xbfb8aa3b, v121
	v_exp_f32_e32 v116, v116
	v_exp_f32_e32 v122, v121
	v_pk_mul_f32 v[112:113], v[112:113], v[120:121] op_sel_hi:[1,0]
	v_pk_mul_f32 v[110:111], v[110:111], v[114:115]
	v_pk_mul_f32 v[108:109], v[108:109], v[112:113]
	v_pk_add_f32 v[112:113], v[116:117], 1.0 op_sel_hi:[1,0]
	v_pk_add_f32 v[116:117], v[122:123], 1.0 op_sel_hi:[1,0]
	v_mul_f32_e32 v120, v113, v112
	v_mul_f32_e32 v121, v117, v116
	v_pk_mul_f32 v[102:103], v[110:111], v[102:103]
	v_mul_f32_e32 v122, v120, v121
	v_rcp_f32_e32 v122, v122
	v_pk_mul_f32 v[100:101], v[108:109], v[100:101]
	s_mov_b32 s26, s16
	s_mov_b64 s[30:31], s[24:25]
	v_mul_f32_e32 v108, v121, v122
	v_mul_f32_e32 v110, v120, v122
	v_pk_mul_f32 v[110:111], v[116:117], v[110:111] op_sel_hi:[1,0]
	v_pk_mul_f32 v[108:109], v[112:113], v[108:109] op_sel_hi:[1,0]
	v_pk_mul_f32 v[106:107], v[106:107], v[110:111]
	v_pk_mul_f32 v[104:105], v[104:105], v[108:109]
	v_pk_mul_f32 v[106:107], v[106:107], v[98:99]
	v_pk_mul_f32 v[98:99], v[104:105], v[96:97]
	v_cvt_pk_bf16_f32 v96, v100, v101
	v_cvt_pk_bf16_f32 v97, v102, v103
	v_max_f32_e32 v100, 0xc1a00000, v92
	v_max_f32_e32 v102, 0xc1a00000, v94
	v_mul_f32_e32 v100, 0xbfb8aa3b, v100
	v_mul_f32_e32 v102, 0xbfb8aa3b, v102
	v_exp_f32_e32 v101, v100
	v_exp_f32_e32 v103, v102
	v_max_f32_e32 v100, 0xc1a00000, v93
	v_max_f32_e32 v102, 0xc1a00000, v95
	v_mul_f32_e32 v100, 0xbfb8aa3b, v100
	v_mul_f32_e32 v102, 0xbfb8aa3b, v102
	v_exp_f32_e32 v100, v100
	v_exp_f32_e32 v102, v102
	v_cvt_pk_bf16_f32 v98, v98, v99
	v_cvt_pk_bf16_f32 v99, v106, v107
	global_store_dwordx4 v[118:119], v[96:99], off
; __device__ __forceinline__ unsigned cvt_pk_bf16(float lo, float hi) { unsigned r; asm volatile("v_cvt_pk_bf16_f32 %0, %1, %2" : "=v"(r) : "v"(lo), "v"(hi)); return r; }
; __device__ __forceinline__ f32x4 sigmoid4(f32x4 x) {
;     f32x4 d;
; #pragma unroll
;     for (int j = 0; j < 4; ++j) d[j] = 1.0f + __expf(-fmaxf(x[j], -20.0f));
;     const float p01 = d[0] * d[1], p23 = d[2] * d[3], r = __builtin_amdgcn_rcpf(p01 * p23), r01 = r * p23, r23 = r * p01;
;     return (f32x4){r01 * d[1], r01 * d[0], r23 * d[3], r23 * d[2]};
; }
;     __device__ __forceinline__ void operator()(const f32x4 (&acc)[2][2][4][2], const Unit& u, int wr, int wc, int fr, int fq) const {
;         const int row0 = u.pm * BM + wr * 64 + fr, col0 = u.pn * HALF + wc * 32 + 8 * fq;
; #pragma unroll
;         for (int ai = 0; ai < 2; ++ai)
; #pragma unroll
;             for (int m = 0; m < 4; ++m) { bf16_t* rowp = O + (size_t)(row0 + ai * HALF + m * 16) * ldc + col0;
;                 f32x4 v0, v1;
; #pragma unroll
;                 for (int j = 0; j < 1; ++j) { v0 = acc[ai][0][m][0] * sigmoid4(acc[ai][0][m][0]) * acc[ai][1][m][0]; v1 = acc[ai][0][m][1] * sigmoid4(acc[ai][0][m][1]) * acc[ai][1][m][1]; }
;                 u32x4 w; w.x = cvt_pk_bf16(v0[0], v0[1]); w.y = cvt_pk_bf16(v0[2], v0[3]); w.z = cvt_pk_bf16(v1[0], v1[1]); w.w = cvt_pk_bf16(v1[2], v1[3]);
;                 *(u32x4*)rowp = w; }
	v_or_b32_e32 v104, 32, v155
	s_nop 0
	v_pk_add_f32 v[96:97], v[100:101], 1.0 op_sel_hi:[1,0]
	v_pk_add_f32 v[98:99], v[102:103], 1.0 op_sel_hi:[1,0]
	v_mul_f32_e32 v100, v97, v96
	v_mul_f32_e32 v101, v99, v98
	s_nop 0
	v_mul_f32_e32 v102, v100, v101
	v_rcp_f32_e32 v105, v102
	v_mad_i64_i32 v[102:103], s[28:29], v104, s52, v[144:145]
	v_lshl_add_u64 v[102:103], v[102:103], 0, v[146:147]
	v_mul_f32_e32 v100, v100, v105
	v_mul_f32_e32 v104, v101, v105
	v_pk_mul_f32 v[98:99], v[98:99], v[100:101] op_sel_hi:[1,0]
	v_max_f32_e32 v100, 0xc1a00000, v88
	v_max_f32_e32 v105, 0xc1a00000, v90
	v_mul_f32_e32 v100, 0xbfb8aa3b, v100
	v_mul_f32_e32 v105, 0xbfb8aa3b, v105
	v_exp_f32_e32 v101, v100
	v_exp_f32_e32 v107, v105
	v_max_f32_e32 v100, 0xc1a00000, v89
	v_max_f32_e32 v105, 0xc1a00000, v91
	v_mul_f32_e32 v100, 0xbfb8aa3b, v100
	v_mul_f32_e32 v105, 0xbfb8aa3b, v105
	v_exp_f32_e32 v100, v100
	v_exp_f32_e32 v106, v105
	v_pk_mul_f32 v[96:97], v[96:97], v[104:105] op_sel_hi:[1,0]
	v_pk_mul_f32 v[94:95], v[94:95], v[98:99]
	v_pk_mul_f32 v[92:93], v[92:93], v[96:97]
	v_pk_add_f32 v[96:97], v[100:101], 1.0 op_sel_hi:[1,0]
	v_pk_add_f32 v[100:101], v[106:107], 1.0 op_sel_hi:[1,0]
	v_mul_f32_e32 v104, v97, v96
	v_mul_f32_e32 v105, v101, v100
	v_pk_mul_f32 v[86:87], v[94:95], v[86:87]
	v_mul_f32_e32 v106, v104, v105
	v_rcp_f32_e32 v106, v106
	v_pk_mul_f32 v[84:85], v[92:93], v[84:85]
	v_mul_f32_e32 v92, v105, v106
	v_mul_f32_e32 v94, v104, v106
	v_pk_mul_f32 v[94:95], v[100:101], v[94:95] op_sel_hi:[1,0]
	v_pk_mul_f32 v[92:93], v[96:97], v[92:93] op_sel_hi:[1,0]
	v_pk_mul_f32 v[90:91], v[90:91], v[94:95]
	v_pk_mul_f32 v[88:89], v[88:89], v[92:93]
	v_pk_mul_f32 v[90:91], v[90:91], v[82:83]
	v_pk_mul_f32 v[82:83], v[88:89], v[80:81]
	v_cvt_pk_bf16_f32 v80, v84, v85
	v_cvt_pk_bf16_f32 v81, v86, v87
	v_max_f32_e32 v84, 0xc1a00000, v76
	v_max_f32_e32 v86, 0xc1a00000, v78
	v_mul_f32_e32 v84, 0xbfb8aa3b, v84
	v_mul_f32_e32 v86, 0xbfb8aa3b, v86
	v_exp_f32_e32 v85, v84
	v_exp_f32_e32 v87, v86
	v_max_f32_e32 v84, 0xc1a00000, v77
	v_max_f32_e32 v86, 0xc1a00000, v79
	v_mul_f32_e32 v84, 0xbfb8aa3b, v84
	v_mul_f32_e32 v86, 0xbfb8aa3b, v86
	v_exp_f32_e32 v84, v84
	v_exp_f32_e32 v86, v86
	v_cvt_pk_bf16_f32 v82, v82, v83
	v_cvt_pk_bf16_f32 v83, v90, v91
	global_store_dwordx4 v[102:103], v[80:83], off
	v_or_b32_e32 v88, 48, v155
	s_nop 0
	v_pk_add_f32 v[80:81], v[84:85], 1.0 op_sel_hi:[1,0]
	v_pk_add_f32 v[82:83], v[86:87], 1.0 op_sel_hi:[1,0]
	v_mul_f32_e32 v84, v81, v80
	v_mul_f32_e32 v85, v83, v82
	s_nop 0
	v_mul_f32_e32 v86, v84, v85
	v_rcp_f32_e32 v89, v86
	v_mad_i64_i32 v[86:87], s[28:29], v88, s52, v[144:145]
	v_lshl_add_u64 v[86:87], v[86:87], 0, v[146:147]
	v_mul_f32_e32 v84, v84, v89
	v_mul_f32_e32 v88, v85, v89
	v_pk_mul_f32 v[82:83], v[82:83], v[84:85] op_sel_hi:[1,0]
	v_max_f32_e32 v84, 0xc1a00000, v72
	v_max_f32_e32 v89, 0xc1a00000, v74
	v_mul_f32_e32 v84, 0xbfb8aa3b, v84
	v_mul_f32_e32 v89, 0xbfb8aa3b, v89
	v_exp_f32_e32 v85, v84
	v_exp_f32_e32 v91, v89
	v_max_f32_e32 v84, 0xc1a00000, v73
	v_max_f32_e32 v89, 0xc1a00000, v75
	v_mul_f32_e32 v84, 0xbfb8aa3b, v84
	v_mul_f32_e32 v89, 0xbfb8aa3b, v89
	v_exp_f32_e32 v84, v84
	v_exp_f32_e32 v90, v89
	v_pk_mul_f32 v[80:81], v[80:81], v[88:89] op_sel_hi:[1,0]
	v_pk_mul_f32 v[78:79], v[78:79], v[82:83]
	v_pk_mul_f32 v[76:77], v[76:77], v[80:81]
	v_pk_add_f32 v[80:81], v[84:85], 1.0 op_sel_hi:[1,0]
	v_pk_add_f32 v[84:85], v[90:91], 1.0 op_sel_hi:[1,0]
	v_mul_f32_e32 v88, v81, v80
	v_mul_f32_e32 v89, v85, v84
	v_pk_mul_f32 v[70:71], v[78:79], v[70:71]
	v_mul_f32_e32 v90, v88, v89
	v_rcp_f32_e32 v90, v90
	v_pk_mul_f32 v[68:69], v[76:77], v[68:69]
	v_mul_f32_e32 v76, v89, v90
	v_mul_f32_e32 v78, v88, v90
	v_pk_mul_f32 v[78:79], v[84:85], v[78:79] op_sel_hi:[1,0]
	v_pk_mul_f32 v[76:77], v[80:81], v[76:77] op_sel_hi:[1,0]
	v_pk_mul_f32 v[74:75], v[74:75], v[78:79]
	v_pk_mul_f32 v[72:73], v[72:73], v[76:77]
	v_pk_mul_f32 v[74:75], v[74:75], v[66:67]
	v_pk_mul_f32 v[66:67], v[72:73], v[64:65]
	v_cvt_pk_bf16_f32 v64, v68, v69
	v_cvt_pk_bf16_f32 v65, v70, v71
	v_max_f32_e32 v68, 0xc1a00000, v60
	v_max_f32_e32 v70, 0xc1a00000, v62
	v_mul_f32_e32 v68, 0xbfb8aa3b, v68
	v_mul_f32_e32 v70, 0xbfb8aa3b, v70
	v_exp_f32_e32 v69, v68
	v_exp_f32_e32 v71, v70
	v_max_f32_e32 v68, 0xc1a00000, v61
	v_max_f32_e32 v70, 0xc1a00000, v63
	v_mul_f32_e32 v68, 0xbfb8aa3b, v68
	v_mul_f32_e32 v70, 0xbfb8aa3b, v70
	v_exp_f32_e32 v68, v68
	v_exp_f32_e32 v70, v70
	v_cvt_pk_bf16_f32 v66, v66, v67
	v_cvt_pk_bf16_f32 v67, v74, v75
	global_store_dwordx4 v[86:87], v[64:67], off
	v_add_u32_e32 v72, 0x80, v155
	s_nop 0
	v_pk_add_f32 v[64:65], v[68:69], 1.0 op_sel_hi:[1,0]
	v_pk_add_f32 v[66:67], v[70:71], 1.0 op_sel_hi:[1,0]
	v_mul_f32_e32 v68, v65, v64
	v_mul_f32_e32 v69, v67, v66
	s_nop 0
	v_mul_f32_e32 v70, v68, v69
	v_rcp_f32_e32 v73, v70
	v_mad_i64_i32 v[70:71], s[28:29], v72, s52, v[144:145]
	v_lshl_add_u64 v[70:71], v[70:71], 0, v[146:147]
	v_mul_f32_e32 v68, v68, v73
	v_mul_f32_e32 v72, v69, v73
	v_pk_mul_f32 v[66:67], v[66:67], v[68:69] op_sel_hi:[1,0]
	v_max_f32_e32 v68, 0xc1a00000, v56
	v_max_f32_e32 v73, 0xc1a00000, v58
	v_mul_f32_e32 v68, 0xbfb8aa3b, v68
	v_mul_f32_e32 v73, 0xbfb8aa3b, v73
	v_exp_f32_e32 v69, v68
	v_exp_f32_e32 v75, v73
	v_max_f32_e32 v68, 0xc1a00000, v57
	v_max_f32_e32 v73, 0xc1a00000, v59
	v_mul_f32_e32 v68, 0xbfb8aa3b, v68
	v_mul_f32_e32 v73, 0xbfb8aa3b, v73
	v_exp_f32_e32 v68, v68
	v_exp_f32_e32 v74, v73
	v_pk_mul_f32 v[64:65], v[64:65], v[72:73] op_sel_hi:[1,0]
	v_pk_mul_f32 v[62:63], v[62:63], v[66:67]
	v_pk_mul_f32 v[60:61], v[60:61], v[64:65]
	v_pk_add_f32 v[64:65], v[68:69], 1.0 op_sel_hi:[1,0]
	v_pk_add_f32 v[68:69], v[74:75], 1.0 op_sel_hi:[1,0]
; __device__ __forceinline__ unsigned cvt_pk_bf16(float lo, float hi) { unsigned r; asm volatile("v_cvt_pk_bf16_f32 %0, %1, %2" : "=v"(r) : "v"(lo), "v"(hi)); return r; }
; __device__ __forceinline__ f32x4 sigmoid4(f32x4 x) {
;     f32x4 d;
; #pragma unroll
;     for (int j = 0; j < 4; ++j) d[j] = 1.0f + __expf(-fmaxf(x[j], -20.0f));
;     const float p01 = d[0] * d[1], p23 = d[2] * d[3], r = __builtin_amdgcn_rcpf(p01 * p23), r01 = r * p23, r23 = r * p01;
;     return (f32x4){r01 * d[1], r01 * d[0], r23 * d[3], r23 * d[2]};
; }
;     __device__ __forceinline__ void operator()(const f32x4 (&acc)[2][2][4][2], const Unit& u, int wr, int wc, int fr, int fq) const {
;         const int row0 = u.pm * BM + wr * 64 + fr, col0 = u.pn * HALF + wc * 32 + 8 * fq;
; #pragma unroll
;         for (int ai = 0; ai < 2; ++ai)
; #pragma unroll
;             for (int m = 0; m < 4; ++m) { bf16_t* rowp = O + (size_t)(row0 + ai * HALF + m * 16) * ldc + col0;
;                 f32x4 v0, v1;
; #pragma unroll
;                 for (int j = 0; j < 1; ++j) { v0 = acc[ai][0][m][0] * sigmoid4(acc[ai][0][m][0]) * acc[ai][1][m][0]; v1 = acc[ai][0][m][1] * sigmoid4(acc[ai][0][m][1]) * acc[ai][1][m][1]; }
;                 u32x4 w; w.x = cvt_pk_bf16(v0[0], v0[1]); w.y = cvt_pk_bf16(v0[2], v0[3]); w.z = cvt_pk_bf16(v1[0], v1[1]); w.w = cvt_pk_bf16(v1[2], v1[3]);
;                 *(u32x4*)rowp = w; }
	v_mul_f32_e32 v72, v65, v64
	v_mul_f32_e32 v73, v69, v68
	v_pk_mul_f32 v[54:55], v[62:63], v[54:55]
	v_mul_f32_e32 v74, v72, v73
	v_rcp_f32_e32 v74, v74
	v_pk_mul_f32 v[52:53], v[60:61], v[52:53]
	v_mul_f32_e32 v60, v73, v74
	v_mul_f32_e32 v62, v72, v74
	v_pk_mul_f32 v[62:63], v[68:69], v[62:63] op_sel_hi:[1,0]
	v_pk_mul_f32 v[60:61], v[64:65], v[60:61] op_sel_hi:[1,0]
	v_pk_mul_f32 v[58:59], v[58:59], v[62:63]
	v_pk_mul_f32 v[56:57], v[56:57], v[60:61]
	v_pk_mul_f32 v[58:59], v[58:59], v[50:51]
	v_pk_mul_f32 v[50:51], v[56:57], v[48:49]
	v_cvt_pk_bf16_f32 v48, v52, v53
	v_cvt_pk_bf16_f32 v49, v54, v55
	v_max_f32_e32 v52, 0xc1a00000, v44
	v_max_f32_e32 v54, 0xc1a00000, v46
	v_mul_f32_e32 v52, 0xbfb8aa3b, v52
	v_mul_f32_e32 v54, 0xbfb8aa3b, v54
	v_exp_f32_e32 v53, v52
	v_exp_f32_e32 v55, v54
	v_max_f32_e32 v52, 0xc1a00000, v45
	v_max_f32_e32 v54, 0xc1a00000, v47
	v_mul_f32_e32 v52, 0xbfb8aa3b, v52
	v_mul_f32_e32 v54, 0xbfb8aa3b, v54
	v_exp_f32_e32 v52, v52
	v_exp_f32_e32 v54, v54
	v_cvt_pk_bf16_f32 v50, v50, v51
	v_cvt_pk_bf16_f32 v51, v58, v59
	global_store_dwordx4 v[70:71], v[48:51], off
	v_add_u32_e32 v56, 0x90, v155
	s_nop 0
	v_pk_add_f32 v[48:49], v[52:53], 1.0 op_sel_hi:[1,0]
	v_pk_add_f32 v[50:51], v[54:55], 1.0 op_sel_hi:[1,0]
	v_mul_f32_e32 v52, v49, v48
	v_mul_f32_e32 v53, v51, v50
	s_nop 0
	v_mul_f32_e32 v54, v52, v53
	v_rcp_f32_e32 v57, v54
	v_mad_i64_i32 v[54:55], s[28:29], v56, s52, v[144:145]
	v_lshl_add_u64 v[54:55], v[54:55], 0, v[146:147]
	v_mul_f32_e32 v52, v52, v57
	v_mul_f32_e32 v56, v53, v57
	v_pk_mul_f32 v[50:51], v[50:51], v[52:53] op_sel_hi:[1,0]
	v_max_f32_e32 v52, 0xc1a00000, v40
	v_max_f32_e32 v57, 0xc1a00000, v42
	v_mul_f32_e32 v52, 0xbfb8aa3b, v52
	v_mul_f32_e32 v57, 0xbfb8aa3b, v57
	v_exp_f32_e32 v53, v52
	v_exp_f32_e32 v59, v57
	v_max_f32_e32 v52, 0xc1a00000, v41
	v_max_f32_e32 v57, 0xc1a00000, v43
	v_mul_f32_e32 v52, 0xbfb8aa3b, v52
	v_mul_f32_e32 v57, 0xbfb8aa3b, v57
	v_exp_f32_e32 v52, v52
	v_exp_f32_e32 v58, v57
	v_pk_mul_f32 v[48:49], v[48:49], v[56:57] op_sel_hi:[1,0]
	v_pk_mul_f32 v[46:47], v[46:47], v[50:51]
	v_pk_mul_f32 v[44:45], v[44:45], v[48:49]
	v_pk_add_f32 v[48:49], v[52:53], 1.0 op_sel_hi:[1,0]
	v_pk_add_f32 v[52:53], v[58:59], 1.0 op_sel_hi:[1,0]
	v_mul_f32_e32 v56, v49, v48
	v_mul_f32_e32 v57, v53, v52
	v_pk_mul_f32 v[38:39], v[46:47], v[38:39]
	v_mul_f32_e32 v58, v56, v57
	v_rcp_f32_e32 v58, v58
	v_pk_mul_f32 v[36:37], v[44:45], v[36:37]
	v_mul_f32_e32 v44, v57, v58
	v_mul_f32_e32 v46, v56, v58
	v_pk_mul_f32 v[46:47], v[52:53], v[46:47] op_sel_hi:[1,0]
	v_pk_mul_f32 v[44:45], v[48:49], v[44:45] op_sel_hi:[1,0]
	v_pk_mul_f32 v[42:43], v[42:43], v[46:47]
	v_pk_mul_f32 v[40:41], v[40:41], v[44:45]
	v_pk_mul_f32 v[42:43], v[42:43], v[34:35]
	v_pk_mul_f32 v[34:35], v[40:41], v[32:33]
	v_cvt_pk_bf16_f32 v32, v36, v37
	v_cvt_pk_bf16_f32 v33, v38, v39
	v_max_f32_e32 v36, 0xc1a00000, v28
	v_max_f32_e32 v38, 0xc1a00000, v30
	v_mul_f32_e32 v36, 0xbfb8aa3b, v36
	v_mul_f32_e32 v38, 0xbfb8aa3b, v38
	v_exp_f32_e32 v37, v36
	v_exp_f32_e32 v39, v38
	v_max_f32_e32 v36, 0xc1a00000, v29
	v_max_f32_e32 v38, 0xc1a00000, v31
	v_mul_f32_e32 v36, 0xbfb8aa3b, v36
	v_mul_f32_e32 v38, 0xbfb8aa3b, v38
	v_exp_f32_e32 v36, v36
	v_exp_f32_e32 v38, v38
	v_cvt_pk_bf16_f32 v34, v34, v35
	v_cvt_pk_bf16_f32 v35, v42, v43
	global_store_dwordx4 v[54:55], v[32:35], off
	v_add_u32_e32 v40, 0xa0, v155
	s_nop 0
	v_pk_add_f32 v[32:33], v[36:37], 1.0 op_sel_hi:[1,0]
	v_pk_add_f32 v[34:35], v[38:39], 1.0 op_sel_hi:[1,0]
	v_mul_f32_e32 v36, v33, v32
	v_mul_f32_e32 v37, v35, v34
	s_nop 0
	v_mul_f32_e32 v38, v36, v37
	v_rcp_f32_e32 v41, v38
	v_mad_i64_i32 v[38:39], s[28:29], v40, s52, v[144:145]
	v_lshl_add_u64 v[38:39], v[38:39], 0, v[146:147]
	v_mul_f32_e32 v36, v36, v41
	v_mul_f32_e32 v40, v37, v41
; __device__ __forceinline__ unsigned cvt_pk_bf16(float lo, float hi) { unsigned r; asm volatile("v_cvt_pk_bf16_f32 %0, %1, %2" : "=v"(r) : "v"(lo), "v"(hi)); return r; }
; __device__ __forceinline__ f32x4 sigmoid4(f32x4 x) {
;     f32x4 d;
; #pragma unroll
;     for (int j = 0; j < 4; ++j) d[j] = 1.0f + __expf(-fmaxf(x[j], -20.0f));
;     const float p01 = d[0] * d[1], p23 = d[2] * d[3], r = __builtin_amdgcn_rcpf(p01 * p23), r01 = r * p23, r23 = r * p01;
;     return (f32x4){r01 * d[1], r01 * d[0], r23 * d[3], r23 * d[2]};
; }
;     __device__ __forceinline__ void operator()(const f32x4 (&acc)[2][2][4][2], const Unit& u, int wr, int wc, int fr, int fq) const {
;         const int row0 = u.pm * BM + wr * 64 + fr, col0 = u.pn * HALF + wc * 32 + 8 * fq;
; #pragma unroll
;         for (int ai = 0; ai < 2; ++ai)
; #pragma unroll
;             for (int m = 0; m < 4; ++m) { bf16_t* rowp = O + (size_t)(row0 + ai * HALF + m * 16) * ldc + col0;
;                 f32x4 v0, v1;
; #pragma unroll
;                 for (int j = 0; j < 1; ++j) { v0 = acc[ai][0][m][0] * sigmoid4(acc[ai][0][m][0]) * acc[ai][1][m][0]; v1 = acc[ai][0][m][1] * sigmoid4(acc[ai][0][m][1]) * acc[ai][1][m][1]; }
;                 u32x4 w; w.x = cvt_pk_bf16(v0[0], v0[1]); w.y = cvt_pk_bf16(v0[2], v0[3]); w.z = cvt_pk_bf16(v1[0], v1[1]); w.w = cvt_pk_bf16(v1[2], v1[3]);
;                 *(u32x4*)rowp = w; }
	v_pk_mul_f32 v[34:35], v[34:35], v[36:37] op_sel_hi:[1,0]
	v_max_f32_e32 v36, 0xc1a00000, v24
	v_max_f32_e32 v41, 0xc1a00000, v26
	v_mul_f32_e32 v36, 0xbfb8aa3b, v36
	v_mul_f32_e32 v41, 0xbfb8aa3b, v41
	v_exp_f32_e32 v37, v36
	v_exp_f32_e32 v43, v41
	v_max_f32_e32 v36, 0xc1a00000, v25
	v_max_f32_e32 v41, 0xc1a00000, v27
	v_mul_f32_e32 v36, 0xbfb8aa3b, v36
	v_mul_f32_e32 v41, 0xbfb8aa3b, v41
	v_exp_f32_e32 v36, v36
	v_exp_f32_e32 v42, v41
	v_pk_mul_f32 v[32:33], v[32:33], v[40:41] op_sel_hi:[1,0]
	v_pk_mul_f32 v[30:31], v[30:31], v[34:35]
	v_pk_mul_f32 v[28:29], v[28:29], v[32:33]
	v_pk_add_f32 v[32:33], v[36:37], 1.0 op_sel_hi:[1,0]
	v_pk_add_f32 v[36:37], v[42:43], 1.0 op_sel_hi:[1,0]
	v_mul_f32_e32 v40, v33, v32
	v_mul_f32_e32 v41, v37, v36
	v_pk_mul_f32 v[22:23], v[30:31], v[22:23]
	v_mul_f32_e32 v42, v40, v41
	v_rcp_f32_e32 v42, v42
	v_pk_mul_f32 v[20:21], v[28:29], v[20:21]
	v_mul_f32_e32 v28, v41, v42
	v_mul_f32_e32 v30, v40, v42
	v_pk_mul_f32 v[30:31], v[36:37], v[30:31] op_sel_hi:[1,0]
	v_pk_mul_f32 v[28:29], v[32:33], v[28:29] op_sel_hi:[1,0]
	v_pk_mul_f32 v[26:27], v[26:27], v[30:31]
	v_pk_mul_f32 v[24:25], v[24:25], v[28:29]
	v_pk_mul_f32 v[26:27], v[26:27], v[18:19]
	v_pk_mul_f32 v[18:19], v[24:25], v[16:17]
	v_cvt_pk_bf16_f32 v16, v20, v21
	v_cvt_pk_bf16_f32 v17, v22, v23
	v_max_f32_e32 v20, 0xc1a00000, v12
	v_max_f32_e32 v22, 0xc1a00000, v14
	v_mul_f32_e32 v20, 0xbfb8aa3b, v20
	v_mul_f32_e32 v22, 0xbfb8aa3b, v22
	v_exp_f32_e32 v21, v20
	v_exp_f32_e32 v23, v22
	v_max_f32_e32 v20, 0xc1a00000, v13
	v_max_f32_e32 v22, 0xc1a00000, v15
	v_mul_f32_e32 v20, 0xbfb8aa3b, v20
	v_mul_f32_e32 v22, 0xbfb8aa3b, v22
	v_exp_f32_e32 v20, v20
	v_exp_f32_e32 v22, v22
	v_cvt_pk_bf16_f32 v18, v18, v19
	v_cvt_pk_bf16_f32 v19, v26, v27
	global_store_dwordx4 v[38:39], v[16:19], off
	v_add_u32_e32 v24, 0xb0, v155
	s_nop 0
	v_pk_add_f32 v[16:17], v[20:21], 1.0 op_sel_hi:[1,0]
	v_pk_add_f32 v[18:19], v[22:23], 1.0 op_sel_hi:[1,0]
	v_mul_f32_e32 v20, v17, v16
	v_mul_f32_e32 v21, v19, v18
	s_nop 0
	v_mul_f32_e32 v22, v20, v21
	v_rcp_f32_e32 v25, v22
	v_mad_i64_i32 v[22:23], s[28:29], v24, s52, v[144:145]
	v_lshl_add_u64 v[22:23], v[22:23], 0, v[146:147]
	v_mul_f32_e32 v20, v20, v25
	v_mul_f32_e32 v24, v21, v25
	v_pk_mul_f32 v[18:19], v[18:19], v[20:21] op_sel_hi:[1,0]
	v_max_f32_e32 v20, 0xc1a00000, v8
	v_max_f32_e32 v25, 0xc1a00000, v10
	v_mul_f32_e32 v20, 0xbfb8aa3b, v20
	v_mul_f32_e32 v25, 0xbfb8aa3b, v25
	v_exp_f32_e32 v21, v20
	v_exp_f32_e32 v27, v25
	v_max_f32_e32 v20, 0xc1a00000, v9
	v_max_f32_e32 v25, 0xc1a00000, v11
	v_mul_f32_e32 v20, 0xbfb8aa3b, v20
	v_mul_f32_e32 v25, 0xbfb8aa3b, v25
	v_exp_f32_e32 v20, v20
	v_exp_f32_e32 v26, v25
	v_pk_mul_f32 v[16:17], v[16:17], v[24:25] op_sel_hi:[1,0]
	v_pk_mul_f32 v[14:15], v[14:15], v[18:19]
	v_pk_mul_f32 v[12:13], v[12:13], v[16:17]
	v_pk_add_f32 v[16:17], v[20:21], 1.0 op_sel_hi:[1,0]
	v_pk_add_f32 v[20:21], v[26:27], 1.0 op_sel_hi:[1,0]
	v_mul_f32_e32 v24, v17, v16
	v_mul_f32_e32 v25, v21, v20
	v_pk_mul_f32 v[6:7], v[14:15], v[6:7]
	v_mul_f32_e32 v26, v24, v25
	v_rcp_f32_e32 v26, v26
	v_pk_mul_f32 v[4:5], v[12:13], v[4:5]
	s_mov_b64 s[28:29], s[18:19]
	v_mul_f32_e32 v12, v25, v26
	v_mul_f32_e32 v14, v24, v26
	v_pk_mul_f32 v[14:15], v[20:21], v[14:15] op_sel_hi:[1,0]
	v_pk_mul_f32 v[12:13], v[16:17], v[12:13] op_sel_hi:[1,0]
	v_pk_mul_f32 v[10:11], v[10:11], v[14:15]
	v_pk_mul_f32 v[8:9], v[8:9], v[12:13]
	v_pk_mul_f32 v[10:11], v[10:11], v[2:3]
	v_pk_mul_f32 v[2:3], v[8:9], v[0:1]
	v_cvt_pk_bf16_f32 v0, v4, v5
	v_cvt_pk_bf16_f32 v1, v6, v7
	s_nop 0
	v_cvt_pk_bf16_f32 v2, v2, v3
	v_cvt_pk_bf16_f32 v3, v10, v11
	global_store_dwordx4 v[22:23], v[0:3], off
	s_cbranch_vccz .LBB0_192
	s_waitcnt vmcnt(0)
	s_cmpk_gt_u32 s37, 0xff
	s_cbranch_scc1 .LBB0_199
	s_barrier

; #define PG8_STAGE(bufoff, gbase, voff) do { _Pragma("unroll") for (int _i = 0; _i < 2; ++_i) \
;         __builtin_amdgcn_global_load_lds((const unsigned*)((const char*)(gbase) + (voff)[_i]), (PG8_LAS unsigned*)(lds + (bufoff) + ldsw + _i * 8192), 16, 0, 0); } while (0)
; #define PG8_LDA(dst, b, h) do { _Pragma("unroll") for (int m = 0; m < 4; ++m) _Pragma("unroll") for (int k = 0; k < 2; ++k) dst[m][k] = *(const PG8_LAS bf16x8*)(lds + PG8_SA(b, h) + aoff + m * 2048 + k * 1024); } while (0)
; #define PG8_WAIT_V(n) asm volatile("s_waitcnt vmcnt(" #n ")" ::: "memory")
; template <class Epi, class Sched>
; __device__ __forceinline__ void gemm_phase(PG8_LAS unsigned char* lds, const Gemm g, const Sched& S, const Epi& E) {
;     ...
;         for (int t = 0; t < nt; t += 2) {
;             const bool last = (t == nt - 2);
;             const char* a1 = cA + (size_t)(t + 1) * kstep;
;             const char* a2 = last ? nA : cA + (size_t)(t + 2) * kstep; const char* b2 = last ? nB : cB + (size_t)(t + 2) * kstep;
;             const char* a3 = a2 + kstep; const char* b3 = b2 + kstep;
;             if (last && has_next) S.a_ready(nxt);
;             PG8_LDB(B0, 0, 0); PG8_SCHED; PG8_LDA(At, 0, 0); PG8_STAGE(PG8_SA(1, 1), a1 + hstep, voffA);
;             PG8_WAIT_L(8); PG8_BAR; PG8_WAIT_L(0); PG8_MMA(0, 0, At, B0); PG8_BAR; PG8_SCHED;
;             PG8_LDB(B1, 0, 1); PG8_STAGE(PG8_SB(0, 0), b2, voffB);
;             PG8_BAR; PG8_WAIT_L(0); PG8_MMA(0, 1, At, B1); PG8_BAR;
;             PG8_LDA(At, 0, 1); PG8_STAGE(PG8_SA(0, 0), a2, voffA);
;             PG8_BAR; PG8_WAIT_L(0); PG8_MMA(1, 0, At, B0); PG8_BAR; PG8_SCHED;
;             PG8_STAGE(PG8_SB(0, 1), b2 + hstep, voffB);
;             PG8_WAIT_V(6); PG8_BAR; PG8_MMA(1, 1, At, B1); PG8_BAR;
;             PG8_LDB(B0, 1, 0); PG8_SCHED; PG8_LDA(At, 1, 0); PG8_STAGE(PG8_SA(0, 1), a2 + hstep, voffA);
;             PG8_WAIT_L(8); PG8_BAR; PG8_WAIT_L(0); PG8_MMA(0, 0, At, B0); PG8_BAR; PG8_SCHED;
;             PG8_LDB(B1, 1, 1); PG8_STAGE(PG8_SB(1, 0), b3, voffB);
;             PG8_BAR; PG8_WAIT_L(0); PG8_MMA(0, 1, At, B1); PG8_BAR;
;             PG8_LDA(At, 1, 1); PG8_STAGE(PG8_SA(1, 0), a3, voffA);
;             PG8_BAR; PG8_WAIT_L(0); PG8_MMA(1, 0, At, B0); PG8_BAR; PG8_SCHED;
;             PG8_STAGE(PG8_SB(1, 1), b3 + hstep, voffB);
;             PG8_WAIT_V(6); PG8_BAR; PG8_MMA(1, 1, At, B1); PG8_BAR;
.LBB0_1202:
	ds_read_b128 v[144:147], v151
	ds_read_b128 v[154:157], v151 offset:1024
	ds_read_b128 v[158:161], v151 offset:2048
	ds_read_b128 v[162:165], v151 offset:3072
	s_add_u32 s18, s16, 0xfffc0080
	s_addc_u32 s19, s17, -1
	s_cmp_eq_u32 s46, 12
	s_cselect_b32 s21, s9, s19
	s_cselect_b32 s20, s42, s18
	s_cselect_b32 s19, s7, s45
	s_cselect_b32 s18, s43, s44
	s_add_i32 m0, s15, 0xc000
	ds_read_b128 v[166:169], v152
	ds_read_b128 v[170:173], v152 offset:1024
	ds_read_b128 v[182:185], v152 offset:2048
	ds_read_b128 v[190:193], v152 offset:3072
	ds_read_b128 v[194:197], v152 offset:4096
	ds_read_b128 v[198:201], v152 offset:5120
	ds_read_b128 v[202:205], v152 offset:6144
	ds_read_b128 v[206:209], v152 offset:7168
	global_load_lds_dwordx4 v136, s[16:17]
	s_nop 1
	s_add_i32 m0, s15, 0xe000
	s_nop 0
	global_load_lds_dwordx4 v138, s[16:17]
	s_waitcnt lgkmcnt(8)
	ds_read_b128 v[210:213], v153
	ds_read_b128 v[214:217], v153 offset:1024
	ds_read_b128 v[218:221], v153 offset:2048
	ds_read_b128 v[222:225], v153 offset:3072
	s_waitcnt vmcnt(8) lgkmcnt(0)
	s_barrier
	v_mfma_f32_16x16x32_bf16 v[124:127], v[144:147], v[166:169], v[124:127]
	v_mfma_f32_16x16x32_bf16 v[120:123], v[158:161], v[166:169], v[120:123]
	v_mfma_f32_16x16x32_bf16 v[108:111], v[144:147], v[182:185], v[108:111]
	v_mfma_f32_16x16x32_bf16 v[104:107], v[158:161], v[182:185], v[104:107]
	v_mfma_f32_16x16x32_bf16 v[92:95], v[144:147], v[194:197], v[92:95]
	v_mfma_f32_16x16x32_bf16 v[88:91], v[158:161], v[194:197], v[88:91]
	v_mfma_f32_16x16x32_bf16 v[76:79], v[144:147], v[202:205], v[76:79]
	v_mfma_f32_16x16x32_bf16 v[72:75], v[158:161], v[202:205], v[72:75]
	v_mfma_f32_16x16x32_bf16 v[124:127], v[154:157], v[170:173], v[124:127]
	v_mfma_f32_16x16x32_bf16 v[120:123], v[162:165], v[170:173], v[120:123]
	v_mfma_f32_16x16x32_bf16 v[108:111], v[154:157], v[190:193], v[108:111]
	v_mfma_f32_16x16x32_bf16 v[104:107], v[162:165], v[190:193], v[104:107]
	v_mfma_f32_16x16x32_bf16 v[92:95], v[154:157], v[198:201], v[92:95]
	v_mfma_f32_16x16x32_bf16 v[88:91], v[162:165], v[198:201], v[88:91]
	v_mfma_f32_16x16x32_bf16 v[76:79], v[154:157], v[206:209], v[76:79]
	v_mfma_f32_16x16x32_bf16 v[72:75], v[162:165], v[206:209], v[72:75]
	v_mfma_f32_16x16x32_bf16 v[116:119], v[210:213], v[166:169], v[116:119]
	v_mfma_f32_16x16x32_bf16 v[112:115], v[218:221], v[166:169], v[112:115]
	v_mfma_f32_16x16x32_bf16 v[100:103], v[210:213], v[182:185], v[100:103]
	v_mfma_f32_16x16x32_bf16 v[96:99], v[218:221], v[182:185], v[96:99]
	v_mfma_f32_16x16x32_bf16 v[84:87], v[210:213], v[194:197], v[84:87]
	v_mfma_f32_16x16x32_bf16 v[80:83], v[218:221], v[194:197], v[80:83]
	v_mfma_f32_16x16x32_bf16 v[68:71], v[210:213], v[202:205], v[68:71]
	v_mfma_f32_16x16x32_bf16 v[64:67], v[218:221], v[202:205], v[64:67]
	v_mfma_f32_16x16x32_bf16 v[116:119], v[214:217], v[170:173], v[116:119]
	v_mfma_f32_16x16x32_bf16 v[112:115], v[222:225], v[170:173], v[112:115]
	v_mfma_f32_16x16x32_bf16 v[100:103], v[214:217], v[190:193], v[100:103]
	v_mfma_f32_16x16x32_bf16 v[96:99], v[222:225], v[190:193], v[96:99]
	v_mfma_f32_16x16x32_bf16 v[84:87], v[214:217], v[198:201], v[84:87]
	v_mfma_f32_16x16x32_bf16 v[80:83], v[222:225], v[198:201], v[80:83]
	v_mfma_f32_16x16x32_bf16 v[68:71], v[214:217], v[206:209], v[68:71]
	v_mfma_f32_16x16x32_bf16 v[64:67], v[222:225], v[206:209], v[64:67]
	s_barrier
	ds_read_b128 v[166:169], v152 offset:16384
	ds_read_b128 v[170:173], v152 offset:17408
	ds_read_b128 v[182:185], v152 offset:18432
	ds_read_b128 v[190:193], v152 offset:19456
	ds_read_b128 v[194:197], v152 offset:20480
	ds_read_b128 v[198:201], v152 offset:21504
	ds_read_b128 v[202:205], v152 offset:22528
	ds_read_b128 v[206:209], v152 offset:23552
	s_add_i32 s47, s38, s26
	s_add_u32 s98, s18, s4
	s_addc_u32 s99, s19, s5
	s_mov_b32 m0, s47
	s_nop 0
	global_load_lds_dwordx4 v132, s[18:19]
	s_nop 1
	s_add_i32 m0, s47, 0x2000
	s_nop 0
	global_load_lds_dwordx4 v128, s[18:19]
	s_nop 1
	s_mov_b32 m0, s15
	s_add_u32 s100, s20, s4
	s_addc_u32 s101, s21, s5
	global_load_lds_dwordx4 v134, s[20:21]
	s_nop 1
	s_mov_b32 m0, s29
	s_nop 0
	global_load_lds_dwordx4 v130, s[20:21]
	s_add_u32 s48, s18, 0x40000
	s_addc_u32 s49, s19, 0
	s_add_i32 s47, s39, s26
	s_mov_b32 m0, s47
	s_nop 0
	global_load_lds_dwordx4 v132, s[48:49]
	s_nop 1
	s_add_i32 m0, s47, 0x2000
	s_nop 0
	global_load_lds_dwordx4 v128, s[48:49]
	s_waitcnt vmcnt(8) lgkmcnt(0)
	s_barrier
	v_mfma_f32_16x16x32_bf16 v[60:63], v[144:147], v[166:169], v[60:63]
	v_mfma_f32_16x16x32_bf16 v[56:59], v[158:161], v[166:169], v[56:59]
	v_mfma_f32_16x16x32_bf16 v[44:47], v[144:147], v[182:185], v[44:47]
	v_mfma_f32_16x16x32_bf16 v[40:43], v[158:161], v[182:185], v[40:43]
	v_mfma_f32_16x16x32_bf16 v[28:31], v[144:147], v[194:197], v[28:31]
	v_mfma_f32_16x16x32_bf16 v[24:27], v[158:161], v[194:197], v[24:27]
	v_mfma_f32_16x16x32_bf16 v[12:15], v[144:147], v[202:205], v[12:15]
	v_mfma_f32_16x16x32_bf16 v[8:11], v[158:161], v[202:205], v[8:11]
	v_mfma_f32_16x16x32_bf16 v[60:63], v[154:157], v[170:173], v[60:63]
	v_mfma_f32_16x16x32_bf16 v[56:59], v[162:165], v[170:173], v[56:59]
	v_mfma_f32_16x16x32_bf16 v[44:47], v[154:157], v[190:193], v[44:47]
	v_mfma_f32_16x16x32_bf16 v[40:43], v[162:165], v[190:193], v[40:43]
	v_mfma_f32_16x16x32_bf16 v[28:31], v[154:157], v[198:201], v[28:31]
	v_mfma_f32_16x16x32_bf16 v[24:27], v[162:165], v[198:201], v[24:27]
	v_mfma_f32_16x16x32_bf16 v[12:15], v[154:157], v[206:209], v[12:15]
	v_mfma_f32_16x16x32_bf16 v[8:11], v[162:165], v[206:209], v[8:11]
	v_mfma_f32_16x16x32_bf16 v[52:55], v[210:213], v[166:169], v[52:55]
	v_mfma_f32_16x16x32_bf16 v[48:51], v[218:221], v[166:169], v[48:51]
	v_mfma_f32_16x16x32_bf16 v[36:39], v[210:213], v[182:185], v[36:39]
	v_mfma_f32_16x16x32_bf16 v[32:35], v[218:221], v[182:185], v[32:35]
	v_mfma_f32_16x16x32_bf16 v[20:23], v[210:213], v[194:197], v[20:23]
	v_mfma_f32_16x16x32_bf16 v[16:19], v[218:221], v[194:197], v[16:19]
	v_mfma_f32_16x16x32_bf16 v[4:7], v[210:213], v[202:205], v[4:7]
	v_mfma_f32_16x16x32_bf16 v[0:3], v[218:221], v[202:205], v[0:3]
	v_mfma_f32_16x16x32_bf16 v[52:55], v[214:217], v[170:173], v[52:55]
	v_mfma_f32_16x16x32_bf16 v[48:51], v[222:225], v[170:173], v[48:51]
	v_mfma_f32_16x16x32_bf16 v[36:39], v[214:217], v[190:193], v[36:39]
	v_mfma_f32_16x16x32_bf16 v[32:35], v[222:225], v[190:193], v[32:35]
	v_mfma_f32_16x16x32_bf16 v[20:23], v[214:217], v[198:201], v[20:23]
	v_mfma_f32_16x16x32_bf16 v[16:19], v[222:225], v[198:201], v[16:19]
	v_mfma_f32_16x16x32_bf16 v[4:7], v[214:217], v[206:209], v[4:7]
	v_mfma_f32_16x16x32_bf16 v[0:3], v[222:225], v[206:209], v[0:3]
	s_barrier
; #define PG8_STAGE(bufoff, gbase, voff) do { _Pragma("unroll") for (int _i = 0; _i < 2; ++_i) \
;         __builtin_amdgcn_global_load_lds((const unsigned*)((const char*)(gbase) + (voff)[_i]), (PG8_LAS unsigned*)(lds + (bufoff) + ldsw + _i * 8192), 16, 0, 0); } while (0)
; #define PG8_LDA(dst, b, h) do { _Pragma("unroll") for (int m = 0; m < 4; ++m) _Pragma("unroll") for (int k = 0; k < 2; ++k) dst[m][k] = *(const PG8_LAS bf16x8*)(lds + PG8_SA(b, h) + aoff + m * 2048 + k * 1024); } while (0)
; #define PG8_LDB(dst, b, h) do { _Pragma("unroll") for (int n = 0; n < 2; ++n) _Pragma("unroll") for (int k = 0; k < 2; ++k) dst[n][k] = *(const PG8_LAS bf16x8*)(lds + PG8_SB(b, h) + boff + n * 2048 + k * 1024); } while (0)
; #define PG8_WAIT_V(n) asm volatile("s_waitcnt vmcnt(" #n ")" ::: "memory")
; #define PG8_WAIT_L(n) asm volatile("s_waitcnt lgkmcnt(" #n ")" ::: "memory")
; #define PG8_BAR __builtin_amdgcn_s_barrier()
; #define PG8_SCHED __builtin_amdgcn_sched_barrier(0)
; template <class Epi, class Sched>
; __device__ __forceinline__ void gemm_phase(PG8_LAS unsigned char* lds, const Gemm g, const Sched& S, const Epi& E) {
;     ...
;             PG8_LDB(B0, 0, 0); PG8_SCHED; PG8_LDA(At, 0, 0); PG8_STAGE(PG8_SA(1, 1), a1 + hstep, voffA);
;             PG8_WAIT_L(8); PG8_BAR; PG8_WAIT_L(0); PG8_MMA(0, 0, At, B0); PG8_BAR; PG8_SCHED;
;             PG8_LDB(B1, 0, 1); PG8_STAGE(PG8_SB(0, 0), b2, voffB);
;             PG8_BAR; PG8_WAIT_L(0); PG8_MMA(0, 1, At, B1); PG8_BAR;
;             PG8_LDA(At, 0, 1); PG8_STAGE(PG8_SA(0, 0), a2, voffA);
;             PG8_BAR; PG8_WAIT_L(0); PG8_MMA(1, 0, At, B0); PG8_BAR; PG8_SCHED;
;             PG8_STAGE(PG8_SB(0, 1), b2 + hstep, voffB);
;             PG8_WAIT_V(6); PG8_BAR; PG8_MMA(1, 1, At, B1); PG8_BAR;
;             PG8_LDB(B0, 1, 0); PG8_SCHED; PG8_LDA(At, 1, 0); PG8_STAGE(PG8_SA(0, 1), a2 + hstep, voffA);
;             PG8_WAIT_L(8); PG8_BAR; PG8_WAIT_L(0); PG8_MMA(0, 0, At, B0); PG8_BAR; PG8_SCHED;
;             PG8_LDB(B1, 1, 1); PG8_STAGE(PG8_SB(1, 0), b3, voffB);
;             PG8_BAR; PG8_WAIT_L(0); PG8_MMA(0, 1, At, B1); PG8_BAR;
;             PG8_LDA(At, 1, 1); PG8_STAGE(PG8_SA(1, 0), a3, voffA);
;             PG8_BAR; PG8_WAIT_L(0); PG8_MMA(1, 0, At, B0); PG8_BAR; PG8_SCHED;
;             PG8_STAGE(PG8_SB(1, 1), b3 + hstep, voffB);
;             PG8_WAIT_V(6); PG8_BAR; PG8_MMA(1, 1, At, B1); PG8_BAR;
	s_add_i32 s47, 0, 0x18000
	v_add_u32_e32 v162, s47, v149
	ds_read_b128 v[144:147], v162
	ds_read_b128 v[154:157], v162 offset:1024
	ds_read_b128 v[158:161], v162 offset:2048
	ds_read_b128 v[162:165], v162 offset:3072
	s_add_u32 s20, s20, 0x40000
	s_addc_u32 s21, s21, 0
	s_mov_b32 m0, s30
	ds_read_b128 v[166:169], v152 offset:32768
	ds_read_b128 v[170:173], v152 offset:33792
	ds_read_b128 v[182:185], v152 offset:34816
	ds_read_b128 v[190:193], v152 offset:35840
	ds_read_b128 v[194:197], v152 offset:36864
	ds_read_b128 v[198:201], v152 offset:37888
	ds_read_b128 v[202:205], v152 offset:38912
	ds_read_b128 v[206:209], v152 offset:39936
	global_load_lds_dwordx4 v134, s[20:21]
	s_nop 1
	s_mov_b32 m0, s31
	s_nop 0
	global_load_lds_dwordx4 v130, s[20:21]
	s_add_i32 s20, 0, 0x1c000
	v_add_u32_e32 v179, s20, v149
	s_waitcnt lgkmcnt(8)
	ds_read_b128 v[210:213], v179
	ds_read_b128 v[214:217], v179 offset:1024
	ds_read_b128 v[218:221], v179 offset:2048
	ds_read_b128 v[222:225], v179 offset:3072
	s_waitcnt vmcnt(8) lgkmcnt(0)
	s_barrier
	v_mfma_f32_16x16x32_bf16 v[124:127], v[144:147], v[166:169], v[124:127]
	v_mfma_f32_16x16x32_bf16 v[120:123], v[158:161], v[166:169], v[120:123]
	v_mfma_f32_16x16x32_bf16 v[108:111], v[144:147], v[182:185], v[108:111]
	v_mfma_f32_16x16x32_bf16 v[104:107], v[158:161], v[182:185], v[104:107]
	v_mfma_f32_16x16x32_bf16 v[92:95], v[144:147], v[194:197], v[92:95]
	v_mfma_f32_16x16x32_bf16 v[88:91], v[158:161], v[194:197], v[88:91]
	v_mfma_f32_16x16x32_bf16 v[76:79], v[144:147], v[202:205], v[76:79]
	v_mfma_f32_16x16x32_bf16 v[72:75], v[158:161], v[202:205], v[72:75]
	v_mfma_f32_16x16x32_bf16 v[124:127], v[154:157], v[170:173], v[124:127]
	v_mfma_f32_16x16x32_bf16 v[120:123], v[162:165], v[170:173], v[120:123]
	v_mfma_f32_16x16x32_bf16 v[108:111], v[154:157], v[190:193], v[108:111]
	v_mfma_f32_16x16x32_bf16 v[104:107], v[162:165], v[190:193], v[104:107]
	v_mfma_f32_16x16x32_bf16 v[92:95], v[154:157], v[198:201], v[92:95]
	v_mfma_f32_16x16x32_bf16 v[88:91], v[162:165], v[198:201], v[88:91]
	v_mfma_f32_16x16x32_bf16 v[76:79], v[154:157], v[206:209], v[76:79]
	v_mfma_f32_16x16x32_bf16 v[72:75], v[162:165], v[206:209], v[72:75]
	v_mfma_f32_16x16x32_bf16 v[116:119], v[210:213], v[166:169], v[116:119]
	v_mfma_f32_16x16x32_bf16 v[112:115], v[218:221], v[166:169], v[112:115]
	v_mfma_f32_16x16x32_bf16 v[100:103], v[210:213], v[182:185], v[100:103]
	v_mfma_f32_16x16x32_bf16 v[96:99], v[218:221], v[182:185], v[96:99]
	v_mfma_f32_16x16x32_bf16 v[84:87], v[210:213], v[194:197], v[84:87]
	v_mfma_f32_16x16x32_bf16 v[80:83], v[218:221], v[194:197], v[80:83]
	v_mfma_f32_16x16x32_bf16 v[68:71], v[210:213], v[202:205], v[68:71]
	v_mfma_f32_16x16x32_bf16 v[64:67], v[218:221], v[202:205], v[64:67]
	v_mfma_f32_16x16x32_bf16 v[116:119], v[214:217], v[170:173], v[116:119]
	v_mfma_f32_16x16x32_bf16 v[112:115], v[222:225], v[170:173], v[112:115]
	v_mfma_f32_16x16x32_bf16 v[100:103], v[214:217], v[190:193], v[100:103]
	v_mfma_f32_16x16x32_bf16 v[96:99], v[222:225], v[190:193], v[96:99]
	v_mfma_f32_16x16x32_bf16 v[84:87], v[214:217], v[198:201], v[84:87]
	v_mfma_f32_16x16x32_bf16 v[80:83], v[222:225], v[198:201], v[80:83]
	v_mfma_f32_16x16x32_bf16 v[68:71], v[214:217], v[206:209], v[68:71]
	v_mfma_f32_16x16x32_bf16 v[64:67], v[222:225], v[206:209], v[64:67]
	s_barrier
	ds_read_b128 v[166:169], v152 offset:49152
	ds_read_b128 v[170:173], v152 offset:50176
	ds_read_b128 v[182:185], v152 offset:51200
	ds_read_b128 v[190:193], v152 offset:52224
	ds_read_b128 v[194:197], v152 offset:53248
	ds_read_b128 v[198:201], v152 offset:54272
	ds_read_b128 v[202:205], v152 offset:55296
	ds_read_b128 v[206:209], v152 offset:56320
	s_add_i32 s21, s47, s26
	s_mov_b32 m0, s21
	s_nop 0
	global_load_lds_dwordx4 v132, s[98:99]
	s_nop 1
	s_add_i32 m0, s21, 0x2000
	s_nop 0
	global_load_lds_dwordx4 v128, s[98:99]
	s_nop 1
	s_mov_b32 m0, s35
	s_nop 0
	global_load_lds_dwordx4 v134, s[100:101]
	s_nop 1
	s_mov_b32 m0, s36
	s_nop 0
	global_load_lds_dwordx4 v130, s[100:101]
	s_add_u32 s18, s18, 0x40080
	s_addc_u32 s19, s19, 0
	s_add_i32 s20, s20, s26
	s_mov_b32 m0, s20
	s_nop 0
	global_load_lds_dwordx4 v132, s[18:19]
	s_nop 1
	s_add_i32 m0, s20, 0x2000
	s_nop 0
	global_load_lds_dwordx4 v128, s[18:19]
	s_waitcnt vmcnt(8) lgkmcnt(0)
	s_barrier
	v_mfma_f32_16x16x32_bf16 v[60:63], v[144:147], v[166:169], v[60:63]
	v_mfma_f32_16x16x32_bf16 v[56:59], v[158:161], v[166:169], v[56:59]
	v_mfma_f32_16x16x32_bf16 v[44:47], v[144:147], v[182:185], v[44:47]
	v_mfma_f32_16x16x32_bf16 v[40:43], v[158:161], v[182:185], v[40:43]
	v_mfma_f32_16x16x32_bf16 v[28:31], v[144:147], v[194:197], v[28:31]
	v_mfma_f32_16x16x32_bf16 v[24:27], v[158:161], v[194:197], v[24:27]
	v_mfma_f32_16x16x32_bf16 v[12:15], v[144:147], v[202:205], v[12:15]
	v_mfma_f32_16x16x32_bf16 v[8:11], v[158:161], v[202:205], v[8:11]
	v_mfma_f32_16x16x32_bf16 v[60:63], v[154:157], v[170:173], v[60:63]
	v_mfma_f32_16x16x32_bf16 v[56:59], v[162:165], v[170:173], v[56:59]
	v_mfma_f32_16x16x32_bf16 v[44:47], v[154:157], v[190:193], v[44:47]
	v_mfma_f32_16x16x32_bf16 v[40:43], v[162:165], v[190:193], v[40:43]
	v_mfma_f32_16x16x32_bf16 v[28:31], v[154:157], v[198:201], v[28:31]
	v_mfma_f32_16x16x32_bf16 v[24:27], v[162:165], v[198:201], v[24:27]
	v_mfma_f32_16x16x32_bf16 v[12:15], v[154:157], v[206:209], v[12:15]
	v_mfma_f32_16x16x32_bf16 v[8:11], v[162:165], v[206:209], v[8:11]
	v_mfma_f32_16x16x32_bf16 v[52:55], v[210:213], v[166:169], v[52:55]
	v_mfma_f32_16x16x32_bf16 v[48:51], v[218:221], v[166:169], v[48:51]
	v_mfma_f32_16x16x32_bf16 v[36:39], v[210:213], v[182:185], v[36:39]
	v_mfma_f32_16x16x32_bf16 v[32:35], v[218:221], v[182:185], v[32:35]
	v_mfma_f32_16x16x32_bf16 v[20:23], v[210:213], v[194:197], v[20:23]
	v_mfma_f32_16x16x32_bf16 v[16:19], v[218:221], v[194:197], v[16:19]
	v_mfma_f32_16x16x32_bf16 v[4:7], v[210:213], v[202:205], v[4:7]
	v_mfma_f32_16x16x32_bf16 v[0:3], v[218:221], v[202:205], v[0:3]
	v_mfma_f32_16x16x32_bf16 v[52:55], v[214:217], v[170:173], v[52:55]
	v_mfma_f32_16x16x32_bf16 v[48:51], v[222:225], v[170:173], v[48:51]
	v_mfma_f32_16x16x32_bf16 v[36:39], v[214:217], v[190:193], v[36:39]
	v_mfma_f32_16x16x32_bf16 v[32:35], v[222:225], v[190:193], v[32:35]
	v_mfma_f32_16x16x32_bf16 v[20:23], v[214:217], v[198:201], v[20:23]
	v_mfma_f32_16x16x32_bf16 v[16:19], v[222:225], v[198:201], v[16:19]
	v_mfma_f32_16x16x32_bf16 v[4:7], v[214:217], v[206:209], v[4:7]
	v_mfma_f32_16x16x32_bf16 v[0:3], v[222:225], v[206:209], v[0:3]
	s_barrier
; __device__ __forceinline__ unsigned cvt_pk_bf16(float lo, float hi) { unsigned r; asm volatile("v_cvt_pk_bf16_f32 %0, %1, %2" : "=v"(r) : "v"(lo), "v"(hi)); return r; }
; __device__ __forceinline__ f32x4 sigmoid4(f32x4 x) {
;     f32x4 d;
; #pragma unroll
;     for (int j = 0; j < 4; ++j) d[j] = 1.0f + __expf(-fmaxf(x[j], -20.0f));
;     const float p01 = d[0] * d[1], p23 = d[2] * d[3], r = __builtin_amdgcn_rcpf(p01 * p23), r01 = r * p23, r23 = r * p01;
;     return (f32x4){r01 * d[1], r01 * d[0], r23 * d[3], r23 * d[2]};
; }
;     __device__ __forceinline__ void operator()(const f32x4 (&acc)[2][2][4][2], const Unit& u, int wr, int wc, int fr, int fq) const {
;         const int row0 = u.pm * BM + wr * 64 + fr, col0 = u.pn * HALF + wc * 32 + 8 * fq;
; #pragma unroll
;         for (int ai = 0; ai < 2; ++ai)
; #pragma unroll
;             for (int m = 0; m < 4; ++m) { bf16_t* rowp = O + (size_t)(row0 + ai * HALF + m * 16) * ldc + col0;
;                 f32x4 v0, v1;
; #pragma unroll
;                 for (int j = 0; j < 1; ++j) { v0 = acc[ai][0][m][0] * sigmoid4(acc[ai][0][m][0]) * acc[ai][1][m][0]; v1 = acc[ai][0][m][1] * sigmoid4(acc[ai][0][m][1]) * acc[ai][1][m][1]; }
;                 u32x4 w; w.x = cvt_pk_bf16(v0[0], v0[1]); w.y = cvt_pk_bf16(v0[2], v0[3]); w.z = cvt_pk_bf16(v1[0], v1[1]); w.w = cvt_pk_bf16(v1[2], v1[3]);
;                 *(u32x4*)rowp = w; }
	s_add_i32 s46, s46, 2
	s_add_u32 s16, s16, 0x100
	s_addc_u32 s17, s17, 0
	s_add_u32 s44, s44, 0x100
	s_addc_u32 s45, s45, 0
	s_cmp_gt_u32 s46, 13
	s_cbranch_scc0 .LBB0_1202
	v_max_f32_e32 v144, 0xc1a00000, v124
	v_mul_f32_e32 v144, 0xbfb8aa3b, v144
	v_exp_f32_e32 v157, v144
	v_max_f32_e32 v144, 0xc1a00000, v125
	v_mul_f32_e32 v144, 0xbfb8aa3b, v144
	v_exp_f32_e32 v156, v144
	v_max_f32_e32 v144, 0xc1a00000, v126
	v_mul_f32_e32 v144, 0xbfb8aa3b, v144
	v_exp_f32_e32 v159, v144
	v_max_f32_e32 v144, 0xc1a00000, v127
	v_mul_f32_e32 v144, 0xbfb8aa3b, v144
	v_exp_f32_e32 v158, v144
	v_pk_add_f32 v[156:157], v[156:157], 1.0 op_sel_hi:[1,0]
	v_lshl_or_b32 v146, s41, 7, v150
	v_pk_add_f32 v[158:159], v[158:159], 1.0 op_sel_hi:[1,0]
	v_mul_f32_e32 v160, v157, v156
	v_mul_f32_e32 v161, v159, v158
	v_lshl_add_u32 v154, s14, 8, v148
	v_mul_f32_e32 v155, v160, v161
	v_rcp_f32_e32 v155, v155
	v_ashrrev_i32_e32 v147, 31, v146
	v_mov_b64_e32 v[144:145], s[0:1]
	v_mad_i64_i32 v[162:163], s[16:17], v154, s40, v[144:145]
	v_mul_f32_e32 v164, v161, v155
	v_mul_f32_e32 v160, v160, v155
	v_max_f32_e32 v155, 0xc1a00000, v120
	v_mul_f32_e32 v155, 0xbfb8aa3b, v155
	v_pk_mul_f32 v[158:159], v[158:159], v[160:161] op_sel_hi:[1,0]
	v_exp_f32_e32 v161, v155
	v_max_f32_e32 v155, 0xc1a00000, v121
	v_mul_f32_e32 v155, 0xbfb8aa3b, v155
	v_exp_f32_e32 v160, v155
	v_max_f32_e32 v155, 0xc1a00000, v122
	v_mul_f32_e32 v155, 0xbfb8aa3b, v155
	v_exp_f32_e32 v167, v155
	v_max_f32_e32 v155, 0xc1a00000, v123
	v_mul_f32_e32 v155, 0xbfb8aa3b, v155
	v_exp_f32_e32 v166, v155
	v_pk_mul_f32 v[156:157], v[156:157], v[164:165] op_sel_hi:[1,0]
	v_pk_mul_f32 v[126:127], v[126:127], v[158:159]
	v_pk_mul_f32 v[124:125], v[124:125], v[156:157]
	v_pk_add_f32 v[156:157], v[160:161], 1.0 op_sel_hi:[1,0]
	v_pk_add_f32 v[160:161], v[166:167], 1.0 op_sel_hi:[1,0]
	v_mul_f32_e32 v164, v157, v156
	v_mul_f32_e32 v165, v161, v160
	v_pk_mul_f32 v[118:119], v[126:127], v[118:119]
	v_mul_f32_e32 v155, v164, v165
	v_rcp_f32_e32 v155, v155
	v_pk_mul_f32 v[116:117], v[124:125], v[116:117]
	v_lshlrev_b64 v[146:147], 1, v[146:147]
	v_lshl_add_u64 v[162:163], v[162:163], 0, v[146:147]
	v_mul_f32_e32 v124, v165, v155
	v_mul_f32_e32 v126, v164, v155
	v_pk_mul_f32 v[126:127], v[160:161], v[126:127] op_sel_hi:[1,0]
	v_pk_mul_f32 v[124:125], v[156:157], v[124:125] op_sel_hi:[1,0]
	v_pk_mul_f32 v[122:123], v[122:123], v[126:127]
	v_pk_mul_f32 v[120:121], v[120:121], v[124:125]
	v_pk_mul_f32 v[122:123], v[122:123], v[114:115]
	v_pk_mul_f32 v[114:115], v[120:121], v[112:113]
	v_cvt_pk_bf16_f32 v112, v116, v117
	v_cvt_pk_bf16_f32 v113, v118, v119
	v_max_f32_e32 v116, 0xc1a00000, v108
	v_max_f32_e32 v118, 0xc1a00000, v110
	v_mul_f32_e32 v116, 0xbfb8aa3b, v116
	v_mul_f32_e32 v118, 0xbfb8aa3b, v118
	v_exp_f32_e32 v117, v116
	v_exp_f32_e32 v119, v118
	v_max_f32_e32 v116, 0xc1a00000, v109
	v_max_f32_e32 v118, 0xc1a00000, v111
	v_mul_f32_e32 v116, 0xbfb8aa3b, v116
	v_mul_f32_e32 v118, 0xbfb8aa3b, v118
	v_exp_f32_e32 v116, v116
	v_exp_f32_e32 v118, v118
	v_cvt_pk_bf16_f32 v114, v114, v115
	v_cvt_pk_bf16_f32 v115, v122, v123
	global_store_dwordx4 v[162:163], v[112:115], off
	v_or_b32_e32 v120, 16, v154
	s_and_b64 vcc, exec, s[2:3]
	v_pk_add_f32 v[112:113], v[116:117], 1.0 op_sel_hi:[1,0]
	v_pk_add_f32 v[114:115], v[118:119], 1.0 op_sel_hi:[1,0]
	v_mul_f32_e32 v116, v113, v112
	v_mul_f32_e32 v117, v115, v114
	s_mov_b32 s41, s6
	v_mul_f32_e32 v118, v116, v117
	v_rcp_f32_e32 v121, v118
	v_mad_i64_i32 v[118:119], s[16:17], v120, s40, v[144:145]
	v_lshl_add_u64 v[118:119], v[118:119], 0, v[146:147]
	v_mul_f32_e32 v116, v116, v121
	v_mul_f32_e32 v120, v117, v121
	v_pk_mul_f32 v[114:115], v[114:115], v[116:117] op_sel_hi:[1,0]
	v_max_f32_e32 v116, 0xc1a00000, v104
	v_max_f32_e32 v121, 0xc1a00000, v106
	v_mul_f32_e32 v116, 0xbfb8aa3b, v116
	v_mul_f32_e32 v121, 0xbfb8aa3b, v121
	v_exp_f32_e32 v117, v116
	v_exp_f32_e32 v123, v121
	v_max_f32_e32 v116, 0xc1a00000, v105
	v_max_f32_e32 v121, 0xc1a00000, v107
	v_mul_f32_e32 v116, 0xbfb8aa3b, v116
	v_mul_f32_e32 v121, 0xbfb8aa3b, v121
	v_exp_f32_e32 v116, v116
	v_exp_f32_e32 v122, v121
	v_pk_mul_f32 v[112:113], v[112:113], v[120:121] op_sel_hi:[1,0]
	v_pk_mul_f32 v[110:111], v[110:111], v[114:115]
	v_pk_mul_f32 v[108:109], v[108:109], v[112:113]
	v_pk_add_f32 v[112:113], v[116:117], 1.0 op_sel_hi:[1,0]
	v_pk_add_f32 v[116:117], v[122:123], 1.0 op_sel_hi:[1,0]
	v_mul_f32_e32 v120, v113, v112
	v_mul_f32_e32 v121, v117, v116
	v_pk_mul_f32 v[102:103], v[110:111], v[102:103]
	v_mul_f32_e32 v122, v120, v121
	v_rcp_f32_e32 v122, v122
	v_pk_mul_f32 v[100:101], v[108:109], v[100:101]
	s_mov_b32 s14, s8
	s_mov_b64 s[18:19], s[12:13]
	v_mul_f32_e32 v108, v121, v122
	v_mul_f32_e32 v110, v120, v122
	v_pk_mul_f32 v[110:111], v[116:117], v[110:111] op_sel_hi:[1,0]
	v_pk_mul_f32 v[108:109], v[112:113], v[108:109] op_sel_hi:[1,0]
	v_pk_mul_f32 v[106:107], v[106:107], v[110:111]
	v_pk_mul_f32 v[104:105], v[104:105], v[108:109]
	v_pk_mul_f32 v[106:107], v[106:107], v[98:99]
	v_pk_mul_f32 v[98:99], v[104:105], v[96:97]
	v_cvt_pk_bf16_f32 v96, v100, v101
	v_cvt_pk_bf16_f32 v97, v102, v103
	v_max_f32_e32 v100, 0xc1a00000, v92
	v_max_f32_e32 v102, 0xc1a00000, v94
	v_mul_f32_e32 v100, 0xbfb8aa3b, v100
	v_mul_f32_e32 v102, 0xbfb8aa3b, v102
	v_exp_f32_e32 v101, v100
	v_exp_f32_e32 v103, v102
	v_max_f32_e32 v100, 0xc1a00000, v93
	v_max_f32_e32 v102, 0xc1a00000, v95
	v_mul_f32_e32 v100, 0xbfb8aa3b, v100
	v_mul_f32_e32 v102, 0xbfb8aa3b, v102
	v_exp_f32_e32 v100, v100
	v_exp_f32_e32 v102, v102
	v_cvt_pk_bf16_f32 v98, v98, v99
	v_cvt_pk_bf16_f32 v99, v106, v107
	global_store_dwordx4 v[118:119], v[96:99], off
; __device__ __forceinline__ unsigned cvt_pk_bf16(float lo, float hi) { unsigned r; asm volatile("v_cvt_pk_bf16_f32 %0, %1, %2" : "=v"(r) : "v"(lo), "v"(hi)); return r; }
; __device__ __forceinline__ f32x4 sigmoid4(f32x4 x) {
;     f32x4 d;
; #pragma unroll
;     for (int j = 0; j < 4; ++j) d[j] = 1.0f + __expf(-fmaxf(x[j], -20.0f));
;     const float p01 = d[0] * d[1], p23 = d[2] * d[3], r = __builtin_amdgcn_rcpf(p01 * p23), r01 = r * p23, r23 = r * p01;
;     return (f32x4){r01 * d[1], r01 * d[0], r23 * d[3], r23 * d[2]};
; }
;     __device__ __forceinline__ void operator()(const f32x4 (&acc)[2][2][4][2], const Unit& u, int wr, int wc, int fr, int fq) const {
;     ...
;         for (int ai = 0; ai < 2; ++ai)
; #pragma unroll
;             for (int m = 0; m < 4; ++m) { bf16_t* rowp = O + (size_t)(row0 + ai * HALF + m * 16) * ldc + col0;
;                 f32x4 v0, v1;
; #pragma unroll
;                 for (int j = 0; j < 1; ++j) { v0 = acc[ai][0][m][0] * sigmoid4(acc[ai][0][m][0]) * acc[ai][1][m][0]; v1 = acc[ai][0][m][1] * sigmoid4(acc[ai][0][m][1]) * acc[ai][1][m][1]; }
;                 u32x4 w; w.x = cvt_pk_bf16(v0[0], v0[1]); w.y = cvt_pk_bf16(v0[2], v0[3]); w.z = cvt_pk_bf16(v1[0], v1[1]); w.w = cvt_pk_bf16(v1[2], v1[3]);
;                 *(u32x4*)rowp = w; }
	v_or_b32_e32 v104, 32, v154
	s_nop 0
	v_pk_add_f32 v[96:97], v[100:101], 1.0 op_sel_hi:[1,0]
	v_pk_add_f32 v[98:99], v[102:103], 1.0 op_sel_hi:[1,0]
	v_mul_f32_e32 v100, v97, v96
	v_mul_f32_e32 v101, v99, v98
	s_nop 0
	v_mul_f32_e32 v102, v100, v101
	v_rcp_f32_e32 v105, v102
	v_mad_i64_i32 v[102:103], s[16:17], v104, s40, v[144:145]
	v_lshl_add_u64 v[102:103], v[102:103], 0, v[146:147]
	v_mul_f32_e32 v100, v100, v105
	v_mul_f32_e32 v104, v101, v105
	v_pk_mul_f32 v[98:99], v[98:99], v[100:101] op_sel_hi:[1,0]
	v_max_f32_e32 v100, 0xc1a00000, v88
	v_max_f32_e32 v105, 0xc1a00000, v90
	v_mul_f32_e32 v100, 0xbfb8aa3b, v100
	v_mul_f32_e32 v105, 0xbfb8aa3b, v105
	v_exp_f32_e32 v101, v100
	v_exp_f32_e32 v107, v105
	v_max_f32_e32 v100, 0xc1a00000, v89
	v_max_f32_e32 v105, 0xc1a00000, v91
	v_mul_f32_e32 v100, 0xbfb8aa3b, v100
	v_mul_f32_e32 v105, 0xbfb8aa3b, v105
	v_exp_f32_e32 v100, v100
	v_exp_f32_e32 v106, v105
	v_pk_mul_f32 v[96:97], v[96:97], v[104:105] op_sel_hi:[1,0]
	v_pk_mul_f32 v[94:95], v[94:95], v[98:99]
	v_pk_mul_f32 v[92:93], v[92:93], v[96:97]
	v_pk_add_f32 v[96:97], v[100:101], 1.0 op_sel_hi:[1,0]
	v_pk_add_f32 v[100:101], v[106:107], 1.0 op_sel_hi:[1,0]
	v_mul_f32_e32 v104, v97, v96
	v_mul_f32_e32 v105, v101, v100
	v_pk_mul_f32 v[86:87], v[94:95], v[86:87]
	v_mul_f32_e32 v106, v104, v105
	v_rcp_f32_e32 v106, v106
	v_pk_mul_f32 v[84:85], v[92:93], v[84:85]
	v_mul_f32_e32 v92, v105, v106
	v_mul_f32_e32 v94, v104, v106
	v_pk_mul_f32 v[94:95], v[100:101], v[94:95] op_sel_hi:[1,0]
	v_pk_mul_f32 v[92:93], v[96:97], v[92:93] op_sel_hi:[1,0]
	v_pk_mul_f32 v[90:91], v[90:91], v[94:95]
	v_pk_mul_f32 v[88:89], v[88:89], v[92:93]
	v_pk_mul_f32 v[90:91], v[90:91], v[82:83]
	v_pk_mul_f32 v[82:83], v[88:89], v[80:81]
	v_cvt_pk_bf16_f32 v80, v84, v85
	v_cvt_pk_bf16_f32 v81, v86, v87
	v_max_f32_e32 v84, 0xc1a00000, v76
	v_max_f32_e32 v86, 0xc1a00000, v78
	v_mul_f32_e32 v84, 0xbfb8aa3b, v84
	v_mul_f32_e32 v86, 0xbfb8aa3b, v86
	v_exp_f32_e32 v85, v84
	v_exp_f32_e32 v87, v86
	v_max_f32_e32 v84, 0xc1a00000, v77
	v_max_f32_e32 v86, 0xc1a00000, v79
	v_mul_f32_e32 v84, 0xbfb8aa3b, v84
	v_mul_f32_e32 v86, 0xbfb8aa3b, v86
	v_exp_f32_e32 v84, v84
	v_exp_f32_e32 v86, v86
	v_cvt_pk_bf16_f32 v82, v82, v83
	v_cvt_pk_bf16_f32 v83, v90, v91
	global_store_dwordx4 v[102:103], v[80:83], off
	v_or_b32_e32 v88, 48, v154
	s_nop 0
	v_pk_add_f32 v[80:81], v[84:85], 1.0 op_sel_hi:[1,0]
	v_pk_add_f32 v[82:83], v[86:87], 1.0 op_sel_hi:[1,0]
	v_mul_f32_e32 v84, v81, v80
	v_mul_f32_e32 v85, v83, v82
	s_nop 0
	v_mul_f32_e32 v86, v84, v85
	v_rcp_f32_e32 v89, v86
	v_mad_i64_i32 v[86:87], s[16:17], v88, s40, v[144:145]
	v_lshl_add_u64 v[86:87], v[86:87], 0, v[146:147]
	v_mul_f32_e32 v84, v84, v89
	v_mul_f32_e32 v88, v85, v89
	v_pk_mul_f32 v[82:83], v[82:83], v[84:85] op_sel_hi:[1,0]
	v_max_f32_e32 v84, 0xc1a00000, v72
	v_max_f32_e32 v89, 0xc1a00000, v74
	v_mul_f32_e32 v84, 0xbfb8aa3b, v84
	v_mul_f32_e32 v89, 0xbfb8aa3b, v89
	v_exp_f32_e32 v85, v84
	v_exp_f32_e32 v91, v89
	v_max_f32_e32 v84, 0xc1a00000, v73
	v_max_f32_e32 v89, 0xc1a00000, v75
	v_mul_f32_e32 v84, 0xbfb8aa3b, v84
	v_mul_f32_e32 v89, 0xbfb8aa3b, v89
	v_exp_f32_e32 v84, v84
	v_exp_f32_e32 v90, v89
	v_pk_mul_f32 v[80:81], v[80:81], v[88:89] op_sel_hi:[1,0]
	v_pk_mul_f32 v[78:79], v[78:79], v[82:83]
	v_pk_mul_f32 v[76:77], v[76:77], v[80:81]
	v_pk_add_f32 v[80:81], v[84:85], 1.0 op_sel_hi:[1,0]
	v_pk_add_f32 v[84:85], v[90:91], 1.0 op_sel_hi:[1,0]
	v_mul_f32_e32 v88, v81, v80
	v_mul_f32_e32 v89, v85, v84
	v_pk_mul_f32 v[70:71], v[78:79], v[70:71]
	v_mul_f32_e32 v90, v88, v89
	v_rcp_f32_e32 v90, v90
	v_pk_mul_f32 v[68:69], v[76:77], v[68:69]
	v_mul_f32_e32 v76, v89, v90
	v_mul_f32_e32 v78, v88, v90
	v_pk_mul_f32 v[78:79], v[84:85], v[78:79] op_sel_hi:[1,0]
	v_pk_mul_f32 v[76:77], v[80:81], v[76:77] op_sel_hi:[1,0]
	v_pk_mul_f32 v[74:75], v[74:75], v[78:79]
	v_pk_mul_f32 v[72:73], v[72:73], v[76:77]
	v_pk_mul_f32 v[74:75], v[74:75], v[66:67]
	v_pk_mul_f32 v[66:67], v[72:73], v[64:65]
	v_cvt_pk_bf16_f32 v64, v68, v69
	v_cvt_pk_bf16_f32 v65, v70, v71
	v_max_f32_e32 v68, 0xc1a00000, v60
	v_max_f32_e32 v70, 0xc1a00000, v62
	v_mul_f32_e32 v68, 0xbfb8aa3b, v68
	v_mul_f32_e32 v70, 0xbfb8aa3b, v70
	v_exp_f32_e32 v69, v68
	v_exp_f32_e32 v71, v70
	v_max_f32_e32 v68, 0xc1a00000, v61
	v_max_f32_e32 v70, 0xc1a00000, v63
	v_mul_f32_e32 v68, 0xbfb8aa3b, v68
	v_mul_f32_e32 v70, 0xbfb8aa3b, v70
	v_exp_f32_e32 v68, v68
	v_exp_f32_e32 v70, v70
	v_cvt_pk_bf16_f32 v66, v66, v67
	v_cvt_pk_bf16_f32 v67, v74, v75
	global_store_dwordx4 v[86:87], v[64:67], off
	v_add_u32_e32 v72, 0x80, v154
	s_nop 0
	v_pk_add_f32 v[64:65], v[68:69], 1.0 op_sel_hi:[1,0]
	v_pk_add_f32 v[66:67], v[70:71], 1.0 op_sel_hi:[1,0]
	v_mul_f32_e32 v68, v65, v64
	v_mul_f32_e32 v69, v67, v66
	s_nop 0
	v_mul_f32_e32 v70, v68, v69
	v_rcp_f32_e32 v73, v70
	v_mad_i64_i32 v[70:71], s[16:17], v72, s40, v[144:145]
	v_lshl_add_u64 v[70:71], v[70:71], 0, v[146:147]
	v_mul_f32_e32 v68, v68, v73
	v_mul_f32_e32 v72, v69, v73
	v_pk_mul_f32 v[66:67], v[66:67], v[68:69] op_sel_hi:[1,0]
	v_max_f32_e32 v68, 0xc1a00000, v56
	v_max_f32_e32 v73, 0xc1a00000, v58
	v_mul_f32_e32 v68, 0xbfb8aa3b, v68
	v_mul_f32_e32 v73, 0xbfb8aa3b, v73
	v_exp_f32_e32 v69, v68
	v_exp_f32_e32 v75, v73
	v_max_f32_e32 v68, 0xc1a00000, v57
	v_max_f32_e32 v73, 0xc1a00000, v59
	v_mul_f32_e32 v68, 0xbfb8aa3b, v68
	v_mul_f32_e32 v73, 0xbfb8aa3b, v73
	v_exp_f32_e32 v68, v68
	v_exp_f32_e32 v74, v73
	v_pk_mul_f32 v[64:65], v[64:65], v[72:73] op_sel_hi:[1,0]
	v_pk_mul_f32 v[62:63], v[62:63], v[66:67]
	v_pk_mul_f32 v[60:61], v[60:61], v[64:65]
	v_pk_add_f32 v[64:65], v[68:69], 1.0 op_sel_hi:[1,0]
	v_pk_add_f32 v[68:69], v[74:75], 1.0 op_sel_hi:[1,0]
; __device__ __forceinline__ unsigned cvt_pk_bf16(float lo, float hi) { unsigned r; asm volatile("v_cvt_pk_bf16_f32 %0, %1, %2" : "=v"(r) : "v"(lo), "v"(hi)); return r; }
; __device__ __forceinline__ f32x4 sigmoid4(f32x4 x) {
;     f32x4 d;
; #pragma unroll
;     for (int j = 0; j < 4; ++j) d[j] = 1.0f + __expf(-fmaxf(x[j], -20.0f));
;     const float p01 = d[0] * d[1], p23 = d[2] * d[3], r = __builtin_amdgcn_rcpf(p01 * p23), r01 = r * p23, r23 = r * p01;
;     return (f32x4){r01 * d[1], r01 * d[0], r23 * d[3], r23 * d[2]};
; }
;     __device__ __forceinline__ void operator()(const f32x4 (&acc)[2][2][4][2], const Unit& u, int wr, int wc, int fr, int fq) const {
;     ...
;         for (int ai = 0; ai < 2; ++ai)
; #pragma unroll
;             for (int m = 0; m < 4; ++m) { bf16_t* rowp = O + (size_t)(row0 + ai * HALF + m * 16) * ldc + col0;
;                 f32x4 v0, v1;
; #pragma unroll
;                 for (int j = 0; j < 1; ++j) { v0 = acc[ai][0][m][0] * sigmoid4(acc[ai][0][m][0]) * acc[ai][1][m][0]; v1 = acc[ai][0][m][1] * sigmoid4(acc[ai][0][m][1]) * acc[ai][1][m][1]; }
;                 u32x4 w; w.x = cvt_pk_bf16(v0[0], v0[1]); w.y = cvt_pk_bf16(v0[2], v0[3]); w.z = cvt_pk_bf16(v1[0], v1[1]); w.w = cvt_pk_bf16(v1[2], v1[3]);
;                 *(u32x4*)rowp = w; }
	v_mul_f32_e32 v72, v65, v64
	v_mul_f32_e32 v73, v69, v68
	v_pk_mul_f32 v[54:55], v[62:63], v[54:55]
	v_mul_f32_e32 v74, v72, v73
	v_rcp_f32_e32 v74, v74
	v_pk_mul_f32 v[52:53], v[60:61], v[52:53]
	v_mul_f32_e32 v60, v73, v74
	v_mul_f32_e32 v62, v72, v74
	v_pk_mul_f32 v[62:63], v[68:69], v[62:63] op_sel_hi:[1,0]
	v_pk_mul_f32 v[60:61], v[64:65], v[60:61] op_sel_hi:[1,0]
	v_pk_mul_f32 v[58:59], v[58:59], v[62:63]
	v_pk_mul_f32 v[56:57], v[56:57], v[60:61]
	v_pk_mul_f32 v[58:59], v[58:59], v[50:51]
	v_pk_mul_f32 v[50:51], v[56:57], v[48:49]
	v_cvt_pk_bf16_f32 v48, v52, v53
	v_cvt_pk_bf16_f32 v49, v54, v55
	v_max_f32_e32 v52, 0xc1a00000, v44
	v_max_f32_e32 v54, 0xc1a00000, v46
	v_mul_f32_e32 v52, 0xbfb8aa3b, v52
	v_mul_f32_e32 v54, 0xbfb8aa3b, v54
	v_exp_f32_e32 v53, v52
	v_exp_f32_e32 v55, v54
	v_max_f32_e32 v52, 0xc1a00000, v45
	v_max_f32_e32 v54, 0xc1a00000, v47
	v_mul_f32_e32 v52, 0xbfb8aa3b, v52
	v_mul_f32_e32 v54, 0xbfb8aa3b, v54
	v_exp_f32_e32 v52, v52
	v_exp_f32_e32 v54, v54
	v_cvt_pk_bf16_f32 v50, v50, v51
	v_cvt_pk_bf16_f32 v51, v58, v59
	global_store_dwordx4 v[70:71], v[48:51], off
	v_add_u32_e32 v56, 0x90, v154
	s_nop 0
	v_pk_add_f32 v[48:49], v[52:53], 1.0 op_sel_hi:[1,0]
	v_pk_add_f32 v[50:51], v[54:55], 1.0 op_sel_hi:[1,0]
	v_mul_f32_e32 v52, v49, v48
	v_mul_f32_e32 v53, v51, v50
	s_nop 0
	v_mul_f32_e32 v54, v52, v53
	v_rcp_f32_e32 v57, v54
	v_mad_i64_i32 v[54:55], s[16:17], v56, s40, v[144:145]
	v_lshl_add_u64 v[54:55], v[54:55], 0, v[146:147]
	v_mul_f32_e32 v52, v52, v57
	v_mul_f32_e32 v56, v53, v57
	v_pk_mul_f32 v[50:51], v[50:51], v[52:53] op_sel_hi:[1,0]
	v_max_f32_e32 v52, 0xc1a00000, v40
	v_max_f32_e32 v57, 0xc1a00000, v42
	v_mul_f32_e32 v52, 0xbfb8aa3b, v52
	v_mul_f32_e32 v57, 0xbfb8aa3b, v57
	v_exp_f32_e32 v53, v52
	v_exp_f32_e32 v59, v57
	v_max_f32_e32 v52, 0xc1a00000, v41
	v_max_f32_e32 v57, 0xc1a00000, v43
	v_mul_f32_e32 v52, 0xbfb8aa3b, v52
	v_mul_f32_e32 v57, 0xbfb8aa3b, v57
	v_exp_f32_e32 v52, v52
	v_exp_f32_e32 v58, v57
	v_pk_mul_f32 v[48:49], v[48:49], v[56:57] op_sel_hi:[1,0]
	v_pk_mul_f32 v[46:47], v[46:47], v[50:51]
	v_pk_mul_f32 v[44:45], v[44:45], v[48:49]
	v_pk_add_f32 v[48:49], v[52:53], 1.0 op_sel_hi:[1,0]
	v_pk_add_f32 v[52:53], v[58:59], 1.0 op_sel_hi:[1,0]
	v_mul_f32_e32 v56, v49, v48
	v_mul_f32_e32 v57, v53, v52
	v_pk_mul_f32 v[38:39], v[46:47], v[38:39]
	v_mul_f32_e32 v58, v56, v57
	v_rcp_f32_e32 v58, v58
	v_pk_mul_f32 v[36:37], v[44:45], v[36:37]
	v_mul_f32_e32 v44, v57, v58
	v_mul_f32_e32 v46, v56, v58
	v_pk_mul_f32 v[46:47], v[52:53], v[46:47] op_sel_hi:[1,0]
	v_pk_mul_f32 v[44:45], v[48:49], v[44:45] op_sel_hi:[1,0]
	v_pk_mul_f32 v[42:43], v[42:43], v[46:47]
	v_pk_mul_f32 v[40:41], v[40:41], v[44:45]
	v_pk_mul_f32 v[42:43], v[42:43], v[34:35]
	v_pk_mul_f32 v[34:35], v[40:41], v[32:33]
	v_cvt_pk_bf16_f32 v32, v36, v37
	v_cvt_pk_bf16_f32 v33, v38, v39
	v_max_f32_e32 v36, 0xc1a00000, v28
	v_max_f32_e32 v38, 0xc1a00000, v30
	v_mul_f32_e32 v36, 0xbfb8aa3b, v36
	v_mul_f32_e32 v38, 0xbfb8aa3b, v38
	v_exp_f32_e32 v37, v36
	v_exp_f32_e32 v39, v38
	v_max_f32_e32 v36, 0xc1a00000, v29
	v_max_f32_e32 v38, 0xc1a00000, v31
	v_mul_f32_e32 v36, 0xbfb8aa3b, v36
	v_mul_f32_e32 v38, 0xbfb8aa3b, v38
	v_exp_f32_e32 v36, v36
	v_exp_f32_e32 v38, v38
	v_cvt_pk_bf16_f32 v34, v34, v35
	v_cvt_pk_bf16_f32 v35, v42, v43
	global_store_dwordx4 v[54:55], v[32:35], off
	v_add_u32_e32 v40, 0xa0, v154
	s_nop 0
	v_pk_add_f32 v[32:33], v[36:37], 1.0 op_sel_hi:[1,0]
	v_pk_add_f32 v[34:35], v[38:39], 1.0 op_sel_hi:[1,0]
	v_mul_f32_e32 v36, v33, v32
	v_mul_f32_e32 v37, v35, v34
	s_nop 0
	v_mul_f32_e32 v38, v36, v37
	v_rcp_f32_e32 v41, v38
	v_mad_i64_i32 v[38:39], s[16:17], v40, s40, v[144:145]
	v_lshl_add_u64 v[38:39], v[38:39], 0, v[146:147]
	v_mul_f32_e32 v36, v36, v41
	v_mul_f32_e32 v40, v37, v41
; __device__ __forceinline__ unsigned cvt_pk_bf16(float lo, float hi) { unsigned r; asm volatile("v_cvt_pk_bf16_f32 %0, %1, %2" : "=v"(r) : "v"(lo), "v"(hi)); return r; }
; __device__ __forceinline__ f32x4 sigmoid4(f32x4 x) {
;     f32x4 d;
; #pragma unroll
;     for (int j = 0; j < 4; ++j) d[j] = 1.0f + __expf(-fmaxf(x[j], -20.0f));
;     const float p01 = d[0] * d[1], p23 = d[2] * d[3], r = __builtin_amdgcn_rcpf(p01 * p23), r01 = r * p23, r23 = r * p01;
;     return (f32x4){r01 * d[1], r01 * d[0], r23 * d[3], r23 * d[2]};
; }
;     __device__ __forceinline__ void operator()(const f32x4 (&acc)[2][2][4][2], const Unit& u, int wr, int wc, int fr, int fq) const {
;     ...
;         for (int ai = 0; ai < 2; ++ai)
; #pragma unroll
;             for (int m = 0; m < 4; ++m) { bf16_t* rowp = O + (size_t)(row0 + ai * HALF + m * 16) * ldc + col0;
;                 f32x4 v0, v1;
; #pragma unroll
;                 for (int j = 0; j < 1; ++j) { v0 = acc[ai][0][m][0] * sigmoid4(acc[ai][0][m][0]) * acc[ai][1][m][0]; v1 = acc[ai][0][m][1] * sigmoid4(acc[ai][0][m][1]) * acc[ai][1][m][1]; }
;                 u32x4 w; w.x = cvt_pk_bf16(v0[0], v0[1]); w.y = cvt_pk_bf16(v0[2], v0[3]); w.z = cvt_pk_bf16(v1[0], v1[1]); w.w = cvt_pk_bf16(v1[2], v1[3]);
;                 *(u32x4*)rowp = w; }
	v_pk_mul_f32 v[34:35], v[34:35], v[36:37] op_sel_hi:[1,0]
	v_max_f32_e32 v36, 0xc1a00000, v24
	v_max_f32_e32 v41, 0xc1a00000, v26
	v_mul_f32_e32 v36, 0xbfb8aa3b, v36
	v_mul_f32_e32 v41, 0xbfb8aa3b, v41
	v_exp_f32_e32 v37, v36
	v_exp_f32_e32 v43, v41
	v_max_f32_e32 v36, 0xc1a00000, v25
	v_max_f32_e32 v41, 0xc1a00000, v27
	v_mul_f32_e32 v36, 0xbfb8aa3b, v36
	v_mul_f32_e32 v41, 0xbfb8aa3b, v41
	v_exp_f32_e32 v36, v36
	v_exp_f32_e32 v42, v41
	v_pk_mul_f32 v[32:33], v[32:33], v[40:41] op_sel_hi:[1,0]
	v_pk_mul_f32 v[30:31], v[30:31], v[34:35]
	v_pk_mul_f32 v[28:29], v[28:29], v[32:33]
	v_pk_add_f32 v[32:33], v[36:37], 1.0 op_sel_hi:[1,0]
	v_pk_add_f32 v[36:37], v[42:43], 1.0 op_sel_hi:[1,0]
	v_mul_f32_e32 v40, v33, v32
	v_mul_f32_e32 v41, v37, v36
	v_pk_mul_f32 v[22:23], v[30:31], v[22:23]
	v_mul_f32_e32 v42, v40, v41
	v_rcp_f32_e32 v42, v42
	v_pk_mul_f32 v[20:21], v[28:29], v[20:21]
	v_mul_f32_e32 v28, v41, v42
	v_mul_f32_e32 v30, v40, v42
	v_pk_mul_f32 v[30:31], v[36:37], v[30:31] op_sel_hi:[1,0]
	v_pk_mul_f32 v[28:29], v[32:33], v[28:29] op_sel_hi:[1,0]
	v_pk_mul_f32 v[26:27], v[26:27], v[30:31]
	v_pk_mul_f32 v[24:25], v[24:25], v[28:29]
	v_pk_mul_f32 v[26:27], v[26:27], v[18:19]
	v_pk_mul_f32 v[18:19], v[24:25], v[16:17]
	v_cvt_pk_bf16_f32 v16, v20, v21
	v_cvt_pk_bf16_f32 v17, v22, v23
	v_max_f32_e32 v20, 0xc1a00000, v12
	v_max_f32_e32 v22, 0xc1a00000, v14
	v_mul_f32_e32 v20, 0xbfb8aa3b, v20
	v_mul_f32_e32 v22, 0xbfb8aa3b, v22
	v_exp_f32_e32 v21, v20
	v_exp_f32_e32 v23, v22
	v_max_f32_e32 v20, 0xc1a00000, v13
	v_max_f32_e32 v22, 0xc1a00000, v15
	v_mul_f32_e32 v20, 0xbfb8aa3b, v20
	v_mul_f32_e32 v22, 0xbfb8aa3b, v22
	v_exp_f32_e32 v20, v20
	v_exp_f32_e32 v22, v22
	v_cvt_pk_bf16_f32 v18, v18, v19
	v_cvt_pk_bf16_f32 v19, v26, v27
	global_store_dwordx4 v[38:39], v[16:19], off
	v_add_u32_e32 v24, 0xb0, v154
	s_nop 0
	v_pk_add_f32 v[16:17], v[20:21], 1.0 op_sel_hi:[1,0]
	v_pk_add_f32 v[18:19], v[22:23], 1.0 op_sel_hi:[1,0]
	v_mul_f32_e32 v20, v17, v16
	v_mul_f32_e32 v21, v19, v18
	s_nop 0
	v_mul_f32_e32 v22, v20, v21
	v_rcp_f32_e32 v25, v22
	v_mad_i64_i32 v[22:23], s[16:17], v24, s40, v[144:145]
	v_lshl_add_u64 v[22:23], v[22:23], 0, v[146:147]
	v_mul_f32_e32 v20, v20, v25
	v_mul_f32_e32 v24, v21, v25
	v_pk_mul_f32 v[18:19], v[18:19], v[20:21] op_sel_hi:[1,0]
	v_max_f32_e32 v20, 0xc1a00000, v8
	v_max_f32_e32 v25, 0xc1a00000, v10
	v_mul_f32_e32 v20, 0xbfb8aa3b, v20
	v_mul_f32_e32 v25, 0xbfb8aa3b, v25
	v_exp_f32_e32 v21, v20
	v_exp_f32_e32 v27, v25
	v_max_f32_e32 v20, 0xc1a00000, v9
	v_max_f32_e32 v25, 0xc1a00000, v11
	v_mul_f32_e32 v20, 0xbfb8aa3b, v20
	v_mul_f32_e32 v25, 0xbfb8aa3b, v25
	v_exp_f32_e32 v20, v20
	v_exp_f32_e32 v26, v25
	v_pk_mul_f32 v[16:17], v[16:17], v[24:25] op_sel_hi:[1,0]
	v_pk_mul_f32 v[14:15], v[14:15], v[18:19]
	v_pk_mul_f32 v[12:13], v[12:13], v[16:17]
	v_pk_add_f32 v[16:17], v[20:21], 1.0 op_sel_hi:[1,0]
	v_pk_add_f32 v[20:21], v[26:27], 1.0 op_sel_hi:[1,0]
	v_mul_f32_e32 v24, v17, v16
	v_mul_f32_e32 v25, v21, v20
	v_pk_mul_f32 v[6:7], v[14:15], v[6:7]
	v_mul_f32_e32 v26, v24, v25
	v_rcp_f32_e32 v26, v26
	v_pk_mul_f32 v[4:5], v[12:13], v[4:5]
	s_mov_b64 s[16:17], s[10:11]
	v_mul_f32_e32 v12, v25, v26
	v_mul_f32_e32 v14, v24, v26
	v_pk_mul_f32 v[14:15], v[20:21], v[14:15] op_sel_hi:[1,0]
	v_pk_mul_f32 v[12:13], v[16:17], v[12:13] op_sel_hi:[1,0]
	v_pk_mul_f32 v[10:11], v[10:11], v[14:15]
	v_pk_mul_f32 v[8:9], v[8:9], v[12:13]
	v_pk_mul_f32 v[10:11], v[10:11], v[2:3]
	v_pk_mul_f32 v[2:3], v[8:9], v[0:1]
	v_cvt_pk_bf16_f32 v0, v4, v5
	v_cvt_pk_bf16_f32 v1, v6, v7
	s_nop 0
	v_cvt_pk_bf16_f32 v2, v2, v3
	v_cvt_pk_bf16_f32 v3, v10, v11
	global_store_dwordx4 v[22:23], v[0:3], off
	s_cbranch_vccz .LBB0_1199
	s_waitcnt vmcnt(0)
	s_cmpk_gt_u32 s23, 0xff
	s_cbranch_scc1 .LBB0_1206
	s_barrier
